# attention staging through LDS-DMA: next item's ctx K/V image loaded during the local half, local V^T image during the ctx pass, local K via registers; end-of-item barrier dropped (on top of all earlie
# speedup vs baseline: 1.0130x; 1.0130x over previous
; __device__ __forceinline__ f32x4 bfx4_lo(u32x4 w) { return (f32x4){bf_lo(w.x), bf_hi(w.x), bf_lo(w.y), bf_hi(w.y)}; }
; __device__ __forceinline__ f32x4 bfx4_hi(u32x4 w) { return (f32x4){bf_lo(w.z), bf_hi(w.z), bf_lo(w.w), bf_hi(w.w)}; }
; __device__ __forceinline__ void phase_rows(const Params& p, const RowArgs& a, int G, int wave, int lane) {
;     ...
;         if (bmaj) mp = (it < ppw) ? (gw / wpb) * (SEQ / 2) + (gw % wpb) + it * wpb : ML / 2 + gw + (it - ppw) * NGW;
;         else mp = ((a.ctx_only && !bmaj) ? ML / 2 : 0) + gw + it * NGW;
;         if (mp >= a.nrows / 2) break;
;         const int m0 = 2 * mp; const bool isl = m0 < ML; const int rb = isl ? (m0 >> 12) : 8;
;         const bool use_y = a.has_y && !(a.lat_no_y && isl);
;         const size_t xoff = isl ? (size_t)m0 * DM : (size_t)(m0 - ML) * DM;
;         const void* xrb = isl ? a.xlat : a.xctx; void* xob = isl ? a.olat : a.octx;
;         bf16_t* xn = XN + (size_t)m0 * DM;
;         const size_t moff = (size_t)rb * NMOD;
;         f32x4 v[2][4], y[2][4];
;         if (a.xin_f32) {
; #pragma unroll
;             for (int u = 0; u < 2; ++u)
; #pragma unroll
;                 for (int j = 0; j < 4; ++j) v[u][j] = *(const f32x4*)((const float*)xrb + xoff + u * DM + 8 * lane + 512 * (j >> 1) + 4 * (j & 1));
;         } else {
; #pragma unroll
;             for (int u = 0; u < 2; ++u)
; #pragma unroll
;                 for (int jb = 0; jb < 2; ++jb) { const u32x4 xw = *(const u32x4*)((const bf16_t*)xrb + xoff + u * DM + 8 * lane + 512 * jb); v[u][2 * jb] = bfx4_lo(xw); v[u][2 * jb + 1] = bfx4_hi(xw); }
;     ...
;                 const float* part = (const float*)p.out;
; #pragma unroll
;                 for (int u = 0; u < 2; ++u)
; #pragma unroll
;                     for (int j = 0; j < 4; ++j) { const float* pp = part + (size_t)(m0 + u - ML) * DM + 8 * lane + 512 * (j >> 1) + 4 * (j & 1); f32x4 s = *(const f32x4*)pp;
; #pragma unroll
;                         for (int k = 1; k < pg8::KSPLIT; ++k) s += *(const f32x4*)(pp + (size_t)k * MC * DM);
;                         y[u][j] = s; }
.LBB0_210:
	s_cmp_ge_i32 s11, s19
	s_mov_b64 s[0:1], -1
	s_cbranch_scc1 .LBB0_204
	s_lshl_b32 s4, s11, 1
	s_cmpk_lt_i32 s11, 0x4000
	s_cselect_b64 s[0:1], -1, 0
	s_ashr_i32 s5, s4, 31
	s_add_i32 s30, s4, 0xffff8000
	s_cmpk_gt_i32 s11, 0x3fff
	s_cselect_b64 s[8:9], -1, 0
	s_and_b64 s[6:7], s[8:9], exec
	s_cselect_b32 s7, 0, s5
	s_cselect_b32 s6, s30, s4
	s_cselect_b32 s23, s99, s79
	s_cselect_b32 s26, s98, s78
	s_lshl_b64 s[24:25], s[6:7], 11
	s_add_u32 s24, s26, s24
	s_addc_u32 s25, s23, s25
	global_load_dwordx4 v[116:119], v170, s[24:25] nt
	global_load_dwordx4 v[112:115], v170, s[24:25] offset:1024 nt
	global_load_dwordx4 v[108:111], v170, s[24:25] offset:2048 nt
	global_load_dwordx4 v[104:107], v170, s[24:25] offset:3072 nt
	s_and_b64 vcc, exec, s[0:1]
	s_cbranch_vccnz .LBB0_213
	s_lshl_b64 s[24:25], s[30:31], 12
	v_lshl_add_u64 v[88:89], v[176:177], 0, s[24:25]
	v_add_co_u32_e32 v96, vcc, 0x800000, v88
	global_load_dwordx4 v[84:87], v[88:89], off offset:16
	global_load_dwordx4 v[80:83], v[88:89], off
	s_mov_b64 s[26:27], 0x800000
	v_addc_co_u32_e32 v97, vcc, 0, v89, vcc
	v_lshl_add_u64 v[94:95], v[88:89], 0, s[26:27]
	global_load_dwordx4 v[90:93], v[96:97], off
	global_load_dwordx4 v[126:129], v[94:95], off offset:16
	s_mov_b64 s[28:29], 0x1000000
	v_add_co_u32_e32 v122, vcc, 0x1000000, v88
	s_mov_b64 s[62:63], 0x1800000
	s_nop 0
	v_addc_co_u32_e32 v123, vcc, 0, v89, vcc
	v_add_co_u32_e32 v120, vcc, 0x1800000, v88
	v_lshl_add_u64 v[100:101], v[88:89], 0, s[62:63]
	s_nop 0
	v_addc_co_u32_e32 v121, vcc, 0, v89, vcc
	v_add_co_u32_e32 v102, vcc, 0x2000000, v88
	s_mov_b64 s[64:65], 0x2000000
	s_nop 0
	v_addc_co_u32_e32 v103, vcc, 0, v89, vcc
	v_add_co_u32_e32 v124, vcc, 0x2800000, v88
	s_mov_b64 s[68:69], 0x2800000
	s_nop 0
	v_addc_co_u32_e32 v125, vcc, 0, v89, vcc
	s_mov_b64 s[70:71], 0x3000000
	v_lshl_add_u64 v[142:143], v[88:89], 0, s[70:71]
	s_mov_b64 s[74:75], 0x3800000
	v_lshl_add_u64 v[146:147], v[88:89], 0, s[74:75]
	s_mov_b64 s[76:77], 0x800800
	s_mov_b64 s[40:41], s[34:35]
	s_mov_b64 s[34:35], 0x1000800
	s_mov_b64 s[86:87], 0x1800800
	s_mov_b64 s[94:95], 0x2000800
	s_mov_b64 s[14:15], 0x2800800
	s_mov_b32 s33, s96
	s_mov_b32 s39, s97
	s_mov_b64 s[96:97], 0x3000800
	s_mov_b64 s[36:37], 0x3800800
	s_add_i32 s30, s4, 0xffff8001
	s_lshl_b64 s[24:25], s[30:31], 12
	s_mov_b32 s23, 0x1000000
	s_waitcnt vmcnt(0)
	v_pk_add_f32 v[98:99], v[82:83], v[92:93]
	v_lshl_add_u64 v[92:93], v[88:89], 0, s[28:29]
	v_pk_add_f32 v[90:91], v[80:81], v[90:91]
	global_load_dwordx4 v[80:83], v[122:123], off
	s_nop 0
	global_load_dwordx4 v[92:95], v[92:93], off offset:16
	v_pk_add_f32 v[86:87], v[86:87], v[128:129]
	v_pk_add_f32 v[84:85], v[84:85], v[126:127]
	s_waitcnt vmcnt(1)
	v_pk_add_f32 v[98:99], v[98:99], v[82:83]
	v_pk_add_f32 v[90:91], v[90:91], v[80:81]
	global_load_dwordx4 v[80:83], v[120:121], off
	global_load_dwordx4 v[130:133], v[100:101], off offset:16
	v_lshl_add_u64 v[100:101], v[88:89], 0, s[64:65]
	s_waitcnt vmcnt(2)
	v_pk_add_f32 v[86:87], v[86:87], v[94:95]
	v_pk_add_f32 v[84:85], v[84:85], v[92:93]
	s_waitcnt vmcnt(1)
	v_pk_add_f32 v[98:99], v[98:99], v[82:83]
	v_pk_add_f32 v[90:91], v[90:91], v[80:81]
	global_load_dwordx4 v[80:83], v[102:103], off
	global_load_dwordx4 v[134:137], v[100:101], off offset:16
	v_lshl_add_u64 v[100:101], v[88:89], 0, s[68:69]
	s_waitcnt vmcnt(2)
	v_pk_add_f32 v[86:87], v[86:87], v[132:133]
	v_pk_add_f32 v[84:85], v[84:85], v[130:131]
	s_waitcnt vmcnt(1)
	v_pk_add_f32 v[98:99], v[98:99], v[82:83]
	v_pk_add_f32 v[90:91], v[90:91], v[80:81]
	global_load_dwordx4 v[80:83], v[124:125], off
	global_load_dwordx4 v[138:141], v[100:101], off offset:16
	v_add_co_u32_e32 v100, vcc, 0x3000000, v88
	s_waitcnt vmcnt(2)
	v_pk_add_f32 v[86:87], v[86:87], v[136:137]
	v_addc_co_u32_e32 v101, vcc, 0, v89, vcc
	v_pk_add_f32 v[84:85], v[84:85], v[134:135]
	s_waitcnt vmcnt(1)
	v_pk_add_f32 v[98:99], v[98:99], v[82:83]
	v_pk_add_f32 v[90:91], v[90:91], v[80:81]
	global_load_dwordx4 v[80:83], v[100:101], off
	s_nop 0
	global_load_dwordx4 v[142:145], v[142:143], off offset:16
	s_waitcnt vmcnt(2)
	v_pk_add_f32 v[84:85], v[84:85], v[138:139]
	v_pk_add_f32 v[86:87], v[86:87], v[140:141]
	s_waitcnt vmcnt(1)
	v_pk_add_f32 v[150:151], v[90:91], v[80:81]
	v_add_co_u32_e32 v90, vcc, 0x3800000, v88
	v_pk_add_f32 v[98:99], v[98:99], v[82:83]
	s_nop 0
	v_addc_co_u32_e32 v91, vcc, 0, v89, vcc
	global_load_dwordx4 v[80:83], v[90:91], off
	s_nop 0
	global_load_dwordx4 v[146:149], v[146:147], off offset:16
	s_nop 0
	global_load_dwordx4 v[92:95], v[88:89], off offset:2064
	global_load_dwordx4 v[126:129], v[88:89], off offset:2048
	s_waitcnt vmcnt(4)
	v_pk_add_f32 v[84:85], v[84:85], v[142:143]
	v_pk_add_f32 v[86:87], v[86:87], v[144:145]
	s_waitcnt vmcnt(3)
	v_pk_add_f32 v[82:83], v[98:99], v[82:83]
	v_lshl_add_u64 v[98:99], v[88:89], 0, s[76:77]
	global_load_dwordx4 v[130:133], v[96:97], off offset:2048
	s_nop 0
	global_load_dwordx4 v[96:99], v[98:99], off offset:16
	s_waitcnt vmcnt(4)
	v_pk_add_f32 v[86:87], v[86:87], v[148:149]
	v_pk_add_f32 v[84:85], v[84:85], v[146:147]
	v_pk_add_f32 v[80:81], v[150:151], v[80:81]
	s_waitcnt vmcnt(1)
	v_pk_add_f32 v[136:137], v[126:127], v[130:131]
	v_lshl_add_u64 v[130:131], v[88:89], 0, s[34:35]
	v_pk_add_f32 v[134:135], v[128:129], v[132:133]
	global_load_dwordx4 v[126:129], v[122:123], off offset:2048
	s_nop 0
	global_load_dwordx4 v[130:133], v[130:131], off offset:16
	s_waitcnt vmcnt(2)
	v_pk_add_f32 v[92:93], v[92:93], v[96:97]
	v_pk_add_f32 v[94:95], v[94:95], v[98:99]
	s_waitcnt vmcnt(1)
; __device__ __forceinline__ void phase_rows(const Params& p, const RowArgs& a, int G, int wave, int lane) {
;     ...
;                 const float* part = (const float*)p.out;
; #pragma unroll
;                 for (int u = 0; u < 2; ++u)
; #pragma unroll
;                     for (int j = 0; j < 4; ++j) { const float* pp = part + (size_t)(m0 + u - ML) * DM + 8 * lane + 512 * (j >> 1) + 4 * (j & 1); f32x4 s = *(const f32x4*)pp;
; #pragma unroll
;                         for (int k = 1; k < pg8::KSPLIT; ++k) s += *(const f32x4*)(pp + (size_t)k * MC * DM);
;                         y[u][j] = s; }
	v_pk_add_f32 v[136:137], v[136:137], v[126:127]
	v_lshl_add_u64 v[126:127], v[88:89], 0, s[86:87]
	v_pk_add_f32 v[134:135], v[134:135], v[128:129]
	global_load_dwordx4 v[120:123], v[120:121], off offset:2048
	s_nop 0
	global_load_dwordx4 v[126:129], v[126:127], off offset:16
	s_waitcnt vmcnt(2)
	v_pk_add_f32 v[92:93], v[92:93], v[130:131]
	v_pk_add_f32 v[94:95], v[94:95], v[132:133]
	s_waitcnt vmcnt(1)
	v_pk_add_f32 v[138:139], v[134:135], v[122:123]
	v_lshl_add_u64 v[134:135], v[88:89], 0, s[94:95]
	v_pk_add_f32 v[140:141], v[136:137], v[120:121]
	global_load_dwordx4 v[120:123], v[102:103], off offset:2048
	s_nop 0
	global_load_dwordx4 v[134:137], v[134:135], off offset:16
	s_waitcnt vmcnt(2)
	v_pk_add_f32 v[92:93], v[92:93], v[126:127]
	v_pk_add_f32 v[94:95], v[94:95], v[128:129]
	s_waitcnt vmcnt(1)
	v_pk_add_f32 v[102:103], v[138:139], v[122:123]
	v_lshl_add_u64 v[138:139], v[88:89], 0, s[14:15]
	v_pk_add_f32 v[142:143], v[140:141], v[120:121]
	global_load_dwordx4 v[120:123], v[124:125], off offset:2048
	s_nop 0
	global_load_dwordx4 v[138:141], v[138:139], off offset:16
	s_waitcnt vmcnt(2)
	v_pk_add_f32 v[92:93], v[92:93], v[134:135]
	v_pk_add_f32 v[94:95], v[94:95], v[136:137]
	s_waitcnt vmcnt(1)
	v_pk_add_f32 v[142:143], v[142:143], v[120:121]
	v_lshl_add_u64 v[120:121], v[88:89], 0, s[96:97]
	v_pk_add_f32 v[124:125], v[102:103], v[122:123]
	global_load_dwordx4 v[100:103], v[100:101], off offset:2048
	s_nop 0
	global_load_dwordx4 v[120:123], v[120:121], off offset:16
	s_waitcnt vmcnt(2)
	v_pk_add_f32 v[92:93], v[92:93], v[138:139]
	v_pk_add_f32 v[94:95], v[94:95], v[140:141]
	s_waitcnt vmcnt(1)
	v_pk_add_f32 v[142:143], v[142:143], v[100:101]
	v_lshl_add_u64 v[100:101], v[88:89], 0, s[36:37]
	v_pk_add_f32 v[124:125], v[124:125], v[102:103]
	global_load_dwordx4 v[88:91], v[90:91], off offset:2048
	s_nop 0
	global_load_dwordx4 v[100:103], v[100:101], off offset:16
	s_waitcnt vmcnt(2)
	v_pk_add_f32 v[92:93], v[92:93], v[120:121]
	v_lshl_add_u64 v[120:121], v[176:177], 0, s[24:25]
	v_pk_add_f32 v[94:95], v[94:95], v[122:123]
	v_add_co_u32_e32 v128, vcc, s55, v120
	v_lshl_add_u64 v[126:127], v[120:121], 0, s[26:27]
	s_nop 0
	v_addc_co_u32_e32 v129, vcc, 0, v121, vcc
	v_add_co_u32_e32 v132, vcc, s23, v120
	s_mov_b32 s23, 0x1800000
	s_nop 0
	v_addc_co_u32_e32 v133, vcc, 0, v121, vcc
	v_add_co_u32_e32 v136, vcc, s23, v120
	v_lshl_add_u64 v[134:135], v[120:121], 0, s[62:63]
	s_nop 0
	v_addc_co_u32_e32 v137, vcc, 0, v121, vcc
	s_brev_b32 s23, 64
	s_waitcnt vmcnt(1)
	v_pk_add_f32 v[90:91], v[124:125], v[90:91]
	s_waitcnt vmcnt(0)
	v_pk_add_f32 v[94:95], v[94:95], v[102:103]
	v_pk_add_f32 v[92:93], v[92:93], v[100:101]
	global_load_dwordx4 v[100:103], v[120:121], off offset:16
	global_load_dwordx4 v[96:99], v[120:121], off
	global_load_dwordx4 v[122:125], v[128:129], off
	global_load_dwordx4 v[138:141], v[126:127], off offset:16
	v_pk_add_f32 v[88:89], v[142:143], v[88:89]
	v_lshl_add_u64 v[142:143], v[120:121], 0, s[64:65]
	s_waitcnt vmcnt(1)
	v_pk_add_f32 v[130:131], v[98:99], v[124:125]
	v_lshl_add_u64 v[124:125], v[120:121], 0, s[28:29]
	v_pk_add_f32 v[122:123], v[96:97], v[122:123]
	global_load_dwordx4 v[96:99], v[132:133], off
	s_nop 0
	global_load_dwordx4 v[124:127], v[124:125], off offset:16
	s_waitcnt vmcnt(2)
	v_pk_add_f32 v[102:103], v[102:103], v[140:141]
	v_pk_add_f32 v[100:101], v[100:101], v[138:139]
	s_waitcnt vmcnt(1)
	v_pk_add_f32 v[130:131], v[130:131], v[98:99]
	v_pk_add_f32 v[122:123], v[122:123], v[96:97]
	global_load_dwordx4 v[96:99], v[136:137], off
	global_load_dwordx4 v[178:181], v[134:135], off offset:16
	s_waitcnt vmcnt(2)
	v_pk_add_f32 v[102:103], v[102:103], v[126:127]
	v_pk_add_f32 v[100:101], v[100:101], v[124:125]
	s_waitcnt vmcnt(1)
	v_pk_add_f32 v[134:135], v[122:123], v[96:97]
	v_add_co_u32_e32 v122, vcc, s23, v120
	v_pk_add_f32 v[130:131], v[130:131], v[98:99]
	s_nop 0
	v_addc_co_u32_e32 v123, vcc, 0, v121, vcc
	global_load_dwordx4 v[96:99], v[122:123], off
	global_load_dwordx4 v[182:185], v[142:143], off offset:16
	s_mov_b32 s23, 0x2800000
	v_add_co_u32_e32 v144, vcc, s23, v120
	v_lshl_add_u64 v[142:143], v[120:121], 0, s[68:69]
	s_nop 0
	v_addc_co_u32_e32 v145, vcc, 0, v121, vcc
	s_mov_b32 s23, 0x3000000
	v_add_co_u32_e32 v148, vcc, s23, v120
	s_mov_b32 s23, 0x3800000
	s_nop 0
	v_addc_co_u32_e32 v149, vcc, 0, v121, vcc
	v_add_co_u32_e32 v152, vcc, s23, v120
	s_waitcnt vmcnt(2)
	v_pk_add_f32 v[102:103], v[102:103], v[180:181]
	v_addc_co_u32_e32 v153, vcc, 0, v121, vcc
	v_pk_add_f32 v[100:101], v[100:101], v[178:179]
	s_waitcnt vmcnt(1)
; __device__ __forceinline__ void phase_rows(const Params& p, const RowArgs& a, int G, int wave, int lane) {
;     ...
;                 const float* part = (const float*)p.out;
; #pragma unroll
;                 for (int u = 0; u < 2; ++u)
; #pragma unroll
;                     for (int j = 0; j < 4; ++j) { const float* pp = part + (size_t)(m0 + u - ML) * DM + 8 * lane + 512 * (j >> 1) + 4 * (j & 1); f32x4 s = *(const f32x4*)pp;
; #pragma unroll
;                         for (int k = 1; k < pg8::KSPLIT; ++k) s += *(const f32x4*)(pp + (size_t)k * MC * DM);
;                         y[u][j] = s; }
	v_pk_add_f32 v[130:131], v[130:131], v[98:99]
	v_pk_add_f32 v[134:135], v[134:135], v[96:97]
	global_load_dwordx4 v[96:99], v[144:145], off
	global_load_dwordx4 v[186:189], v[142:143], off offset:16
	v_lshl_add_u64 v[142:143], v[120:121], 0, s[70:71]
	s_waitcnt vmcnt(2)
	v_pk_add_f32 v[100:101], v[100:101], v[182:183]
	v_pk_add_f32 v[102:103], v[102:103], v[184:185]
	s_waitcnt vmcnt(1)
	v_pk_add_f32 v[130:131], v[130:131], v[98:99]
	v_pk_add_f32 v[134:135], v[134:135], v[96:97]
	global_load_dwordx4 v[96:99], v[148:149], off
	global_load_dwordx4 v[190:193], v[142:143], off offset:16
	v_lshl_add_u64 v[142:143], v[120:121], 0, s[74:75]
	s_waitcnt vmcnt(2)
	v_pk_add_f32 v[102:103], v[102:103], v[188:189]
	v_pk_add_f32 v[100:101], v[100:101], v[186:187]
	s_waitcnt vmcnt(1)
	v_pk_add_f32 v[130:131], v[130:131], v[98:99]
	v_pk_add_f32 v[134:135], v[134:135], v[96:97]
	global_load_dwordx4 v[96:99], v[152:153], off
	global_load_dwordx4 v[194:197], v[142:143], off offset:16
	global_load_dwordx4 v[124:127], v[120:121], off offset:2064
	global_load_dwordx4 v[138:141], v[120:121], off offset:2048
	s_waitcnt vmcnt(4)
	v_pk_add_f32 v[102:103], v[102:103], v[192:193]
	v_pk_add_f32 v[100:101], v[100:101], v[190:191]
	s_waitcnt vmcnt(3)
	v_pk_add_f32 v[98:99], v[130:131], v[98:99]
	v_lshl_add_u64 v[130:131], v[120:121], 0, s[76:77]
	global_load_dwordx4 v[178:181], v[128:129], off offset:2048
	s_nop 0
	global_load_dwordx4 v[128:131], v[130:131], off offset:16
	v_pk_add_f32 v[96:97], v[134:135], v[96:97]
	v_lshl_add_u64 v[134:135], v[120:121], 0, s[34:35]
	s_waitcnt vmcnt(4)
	v_pk_add_f32 v[102:103], v[102:103], v[196:197]
	v_pk_add_f32 v[100:101], v[100:101], v[194:195]
	s_mov_b64 s[34:35], s[40:41]
	s_waitcnt vmcnt(1)
	v_pk_add_f32 v[142:143], v[140:141], v[180:181]
	v_pk_add_f32 v[146:147], v[138:139], v[178:179]
	global_load_dwordx4 v[138:141], v[132:133], off offset:2048
	s_nop 0
	global_load_dwordx4 v[132:135], v[134:135], off offset:16
	s_waitcnt vmcnt(2)
	v_pk_add_f32 v[126:127], v[126:127], v[130:131]
	v_pk_add_f32 v[124:125], v[124:125], v[128:129]
	s_waitcnt vmcnt(1)
	v_pk_add_f32 v[146:147], v[146:147], v[138:139]
	v_lshl_add_u64 v[138:139], v[120:121], 0, s[86:87]
	v_pk_add_f32 v[150:151], v[142:143], v[140:141]
	global_load_dwordx4 v[140:143], v[136:137], off offset:2048
	s_nop 0
	global_load_dwordx4 v[136:139], v[138:139], off offset:16
	s_waitcnt vmcnt(2)
	v_pk_add_f32 v[126:127], v[126:127], v[134:135]
	v_pk_add_f32 v[124:125], v[124:125], v[132:133]
	s_mov_b32 s87, s38
	v_readlane_b32 s86, v255, 11
	s_waitcnt vmcnt(1)
	v_pk_add_f32 v[146:147], v[146:147], v[140:141]
	v_lshl_add_u64 v[140:141], v[120:121], 0, s[94:95]
	v_pk_add_f32 v[150:151], v[150:151], v[142:143]
	global_load_dwordx4 v[178:181], v[122:123], off offset:2048
	s_nop 0
	global_load_dwordx4 v[140:143], v[140:141], off offset:16
	s_waitcnt vmcnt(2)
	v_pk_add_f32 v[126:127], v[126:127], v[138:139]
	v_pk_add_f32 v[124:125], v[124:125], v[136:137]
	v_readlane_b32 s94, v255, 27
	v_readlane_b32 s95, v255, 28
	s_waitcnt vmcnt(1)
	v_pk_add_f32 v[122:123], v[150:151], v[180:181]
	v_pk_add_f32 v[150:151], v[146:147], v[178:179]
	v_lshl_add_u64 v[146:147], v[120:121], 0, s[14:15]
	global_load_dwordx4 v[178:181], v[144:145], off offset:2048
	s_nop 0
	global_load_dwordx4 v[144:147], v[146:147], off offset:16
	s_waitcnt vmcnt(2)
	v_pk_add_f32 v[126:127], v[126:127], v[142:143]
	v_pk_add_f32 v[124:125], v[124:125], v[140:141]
	s_waitcnt vmcnt(1)
	v_pk_add_f32 v[154:155], v[150:151], v[178:179]
	v_lshl_add_u64 v[150:151], v[120:121], 0, s[96:97]
	v_pk_add_f32 v[122:123], v[122:123], v[180:181]
	global_load_dwordx4 v[180:183], v[148:149], off offset:2048
	s_nop 0
	global_load_dwordx4 v[148:151], v[150:151], off offset:16
	s_waitcnt vmcnt(2)
	v_pk_add_f32 v[126:127], v[126:127], v[146:147]
	v_pk_add_f32 v[124:125], v[124:125], v[144:145]
	s_mov_b32 s97, s39
	s_mov_b32 s96, s33
	s_waitcnt vmcnt(1)
	v_pk_add_f32 v[180:181], v[154:155], v[180:181]
	v_lshl_add_u64 v[154:155], v[120:121], 0, s[36:37]
	v_pk_add_f32 v[178:179], v[122:123], v[182:183]
	global_load_dwordx4 v[120:123], v[152:153], off offset:2048
	s_nop 0
	global_load_dwordx4 v[152:155], v[154:155], off offset:16
	s_waitcnt vmcnt(2)
	v_pk_add_f32 v[126:127], v[126:127], v[150:151]
	v_pk_add_f32 v[124:125], v[124:125], v[148:149]
	s_waitcnt vmcnt(1)
	v_pk_add_f32 v[122:123], v[178:179], v[122:123]
	v_pk_add_f32 v[120:121], v[180:181], v[120:121]
	s_waitcnt vmcnt(0)
	v_pk_add_f32 v[126:127], v[126:127], v[154:155]
	v_pk_add_f32 v[124:125], v[124:125], v[152:153]

; #define AH_LDK(c, bufi) do { kf[bufi][0] = *(const LAS bf16x8*)(lds + kaddr0 + (c) * kcs); kf[bufi][1] = *(const LAS bf16x8*)(lds + kaddr1 + (c) * kcs); \
;         kf[bufi][2] = *(const LAS bf16x8*)(lds + kaddr0 + (c) * kcs + 512); kf[bufi][3] = *(const LAS bf16x8*)(lds + kaddr1 + (c) * kcs + 512); } while (0)
; template <bool LOC> ...
;     ...
;     AH_LDK(0, 0);
; #pragma unroll
;     for (int c = 0; c < 8; ++c) {
;         if (c < 7) AH_LDK(c + 1, (c + 1) & 1);
;         __builtin_amdgcn_sched_barrier(0);
;         f32x4 t0 = (f32x4){0.f, 0.f, 0.f, 0.f}, t1 = (f32x4){0.f, 0.f, 0.f, 0.f};
;         t0 = __builtin_amdgcn_mfma_f32_16x16x32_bf16(kf[c & 1][0], q0, t0, 0, 0, 0); t1 = __builtin_amdgcn_mfma_f32_16x16x32_bf16(kf[c & 1][2], q0, t1, 0, 0, 0);
;         t0 = __builtin_amdgcn_mfma_f32_16x16x32_bf16(kf[c & 1][1], q1, t0, 0, 0, 0); t1 = __builtin_amdgcn_mfma_f32_16x16x32_bf16(kf[c & 1][3], q1, t1, 0, 0, 0);
; #pragma unroll
;         for (int e = 0; e < 8; ++e) { const float a = (e < 4) ? t0[e] : t1[e - 4];
;             if (LOC) { const float bv = bp[c * RPB_PITCH + e]; const bool ok = (e >= elo) && (e < elo + 16); s[c][e] = ok ? (a * SC + bv) : -INFINITY; }
;             else s[c][e] = a * SC; }
;         __builtin_amdgcn_sched_barrier(0);
;     }
.LBB0_296:
	s_or_b64 exec, exec, s[68:69]
	v_mov_b32_e32 v216, 0x3e38aa3b
	v_mov_b32_e32 v217, 0x3e38aa3b
	s_add_i32 s64, s64, -4
	s_min_u32 s64, s64, 56
	v_sub_u32_e32 v36, s64, v26
	v_lshl_add_u32 v24, v36, 13, v128
	v_add_u32_e32 v25, v24, v126
	s_waitcnt lgkmcnt(0)
	s_barrier
	v_add_u32_e32 v26, v24, v127
	ds_read_b128 v[30:33], v25
	ds_read_b128 v[38:41], v25 offset:512
	ds_read_b128 v[42:45], v26
	ds_read_b128 v[46:49], v26 offset:512
	ds_read_b128 v[50:53], v25 offset:8192
	ds_read_b128 v[54:57], v25 offset:8704
	ds_read_b128 v[58:61], v26 offset:8192
	ds_read_b128 v[62:65], v26 offset:8704
	s_sub_i32 s63, s64, s63
	v_lshl_add_u32 v24, s63, 8, v129
	v_add_u32_e32 v232, 0x77c, v24
	v_add_u32_e32 v233, 0xb7c, v24
	s_waitcnt lgkmcnt(7)
	v_mfma_f32_16x16x32_bf16 v[30:33], v[30:33], v[4:7], 0
	ds_read2_b32 v[34:35], v232 offset0:0 offset1:1
	s_waitcnt lgkmcnt(5)
	v_mfma_f32_16x16x32_bf16 v[30:33], v[42:45], v[0:3], v[30:33]
	v_mfma_f32_16x16x32_bf16 v[38:41], v[38:41], v[4:7], 0
	v_mfma_f32_16x16x32_bf16 v[38:41], v[46:49], v[0:3], v[38:41]
	ds_read2_b32 v[210:211], v232 offset0:2 offset1:3
	ds_read2_b32 v[212:213], v232 offset0:4 offset1:5
	ds_read2_b32 v[214:215], v232 offset0:6 offset1:7
	s_waitcnt lgkmcnt(0)
	s_nop 3
	v_pk_fma_f32 v[34:35], v[30:31], v[216:217], v[34:35]
	v_cndmask_b32_e64 v30, v222, v34, s[6:7]
	v_cndmask_b32_e64 v29, v222, v35, s[8:9]
	v_pk_fma_f32 v[210:211], v[32:33], v[216:217], v[210:211]
	v_cndmask_b32_e64 v32, v222, v210, s[10:11]
	v_cndmask_b32_e64 v31, v222, v211, s[12:13]
	v_pk_fma_f32 v[212:213], v[38:39], v[216:217], v[212:213]
	v_cndmask_b32_e64 v34, v222, v212, s[14:15]
	v_cndmask_b32_e64 v33, v222, v213, s[16:17]
	v_pk_fma_f32 v[214:215], v[40:41], v[216:217], v[214:215]
	v_cndmask_b32_e64 v43, v222, v214, s[18:19]
	v_cndmask_b32_e64 v41, v222, v215, s[20:21]
	ds_read_b128 v[44:47], v25 offset:16384
	ds_read_b128 v[66:69], v25 offset:16896
	ds_read_b128 v[100:103], v26 offset:16384
	ds_read_b128 v[152:155], v26 offset:16896
	v_mfma_f32_16x16x32_bf16 v[48:51], v[50:53], v[4:7], 0
	ds_read2_b32 v[38:39], v232 offset0:64 offset1:65
	v_mfma_f32_16x16x32_bf16 v[48:51], v[58:61], v[0:3], v[48:51]
	v_mfma_f32_16x16x32_bf16 v[52:55], v[54:57], v[4:7], 0
	v_mfma_f32_16x16x32_bf16 v[52:55], v[62:65], v[0:3], v[52:55]
	ds_read2_b32 v[210:211], v232 offset0:66 offset1:67
	ds_read2_b32 v[212:213], v232 offset0:68 offset1:69
	ds_read2_b32 v[214:215], v232 offset0:70 offset1:71
	s_waitcnt lgkmcnt(0)
	s_nop 4
	v_pk_fma_f32 v[38:39], v[48:49], v[216:217], v[38:39]
	v_cndmask_b32_e64 v37, v222, v38, s[6:7]
	v_cndmask_b32_e64 v35, v222, v39, s[8:9]
	v_pk_fma_f32 v[210:211], v[50:51], v[216:217], v[210:211]
	v_cndmask_b32_e64 v39, v222, v210, s[10:11]
	v_cndmask_b32_e64 v38, v222, v211, s[12:13]
	v_pk_fma_f32 v[212:213], v[52:53], v[216:217], v[212:213]
	v_cndmask_b32_e64 v42, v222, v212, s[14:15]
	v_cndmask_b32_e64 v40, v222, v213, s[16:17]
	v_pk_fma_f32 v[214:215], v[54:55], v[216:217], v[214:215]
	v_cndmask_b32_e64 v51, v222, v214, s[18:19]
	v_cndmask_b32_e64 v49, v222, v215, s[20:21]
	ds_read_b128 v[52:55], v25 offset:24576
	ds_read_b128 v[60:63], v25 offset:25088
	ds_read_b128 v[170:173], v26 offset:24576
	ds_read_b128 v[174:177], v26 offset:25088
	v_mfma_f32_16x16x32_bf16 v[44:47], v[44:47], v[4:7], 0
	v_mfma_f32_16x16x32_bf16 v[56:59], v[66:69], v[4:7], 0
	v_mfma_f32_16x16x32_bf16 v[64:67], v[100:103], v[0:3], v[44:47]
	s_nop 4
	ds_read2_b32 v[46:47], v232 offset0:128 offset1:129
	v_mfma_f32_16x16x32_bf16 v[68:71], v[152:155], v[0:3], v[56:59]
	ds_read2_b32 v[210:211], v232 offset0:130 offset1:131
	ds_read2_b32 v[212:213], v232 offset0:132 offset1:133
	ds_read2_b32 v[214:215], v232 offset0:134 offset1:135
	s_waitcnt lgkmcnt(0)
	v_pk_fma_f32 v[46:47], v[64:65], v[216:217], v[46:47]
	v_cndmask_b32_e64 v45, v222, v46, s[6:7]
	v_cndmask_b32_e64 v44, v222, v47, s[8:9]
	v_pk_fma_f32 v[210:211], v[66:67], v[216:217], v[210:211]
	v_cndmask_b32_e64 v47, v222, v210, s[10:11]
	v_cndmask_b32_e64 v46, v222, v211, s[12:13]
	v_pk_fma_f32 v[212:213], v[68:69], v[216:217], v[212:213]
	v_cndmask_b32_e64 v50, v222, v212, s[14:15]
	v_cndmask_b32_e64 v48, v222, v213, s[16:17]
	v_pk_fma_f32 v[214:215], v[70:71], v[216:217], v[214:215]
	v_cndmask_b32_e64 v59, v222, v214, s[18:19]
	v_cndmask_b32_e64 v57, v222, v215, s[20:21]
	ds_read_b128 v[68:71], v25 offset:32768
	ds_read_b128 v[100:103], v25 offset:33280
	ds_read_b128 v[152:155], v26 offset:32768
	ds_read_b128 v[178:181], v26 offset:33280
	v_mfma_f32_16x16x32_bf16 v[52:55], v[52:55], v[4:7], 0
	v_mfma_f32_16x16x32_bf16 v[64:67], v[170:173], v[0:3], v[52:55]
	v_mfma_f32_16x16x32_bf16 v[60:63], v[60:63], v[4:7], 0
	s_nop 4
	ds_read2_b32 v[54:55], v232 offset0:192 offset1:193
	ds_read2_b32 v[210:211], v232 offset0:194 offset1:195
	ds_read2_b32 v[212:213], v232 offset0:196 offset1:197
	ds_read2_b32 v[214:215], v232 offset0:198 offset1:199
	s_waitcnt lgkmcnt(0)
	v_pk_fma_f32 v[54:55], v[64:65], v[216:217], v[54:55]
	v_cndmask_b32_e64 v53, v222, v54, s[6:7]
	v_cndmask_b32_e64 v52, v222, v55, s[8:9]
	v_mfma_f32_16x16x32_bf16 v[60:63], v[174:177], v[0:3], v[60:63]
	v_pk_fma_f32 v[210:211], v[66:67], v[216:217], v[210:211]
	v_cndmask_b32_e64 v55, v222, v210, s[10:11]
	v_cndmask_b32_e64 v54, v222, v211, s[12:13]
	s_nop 3
	s_nop 0
	v_pk_fma_f32 v[212:213], v[60:61], v[216:217], v[212:213]
	v_cndmask_b32_e64 v58, v222, v212, s[14:15]
	v_cndmask_b32_e64 v56, v222, v213, s[16:17]
	v_pk_fma_f32 v[214:215], v[62:63], v[216:217], v[214:215]
	v_cndmask_b32_e64 v67, v222, v214, s[18:19]
	v_cndmask_b32_e64 v65, v222, v215, s[20:21]
	ds_read_b128 v[170:173], v25 offset:40960
	ds_read_b128 v[174:177], v25 offset:41472
	ds_read_b128 v[182:185], v26 offset:40960
	ds_read_b128 v[186:189], v26 offset:41472
	v_mfma_f32_16x16x32_bf16 v[60:63], v[68:71], v[4:7], 0
	v_mfma_f32_16x16x32_bf16 v[68:71], v[100:103], v[4:7], 0
	v_mfma_f32_16x16x32_bf16 v[100:103], v[152:155], v[0:3], v[60:63]
	s_nop 4
	ds_read2_b32 v[62:63], v233 offset0:0 offset1:1
	v_mfma_f32_16x16x32_bf16 v[68:71], v[178:181], v[0:3], v[68:71]
	ds_read2_b32 v[210:211], v233 offset0:2 offset1:3
	ds_read2_b32 v[212:213], v233 offset0:4 offset1:5
	ds_read2_b32 v[214:215], v233 offset0:6 offset1:7
	s_waitcnt lgkmcnt(0)
; #define LAS __attribute__((address_space(3)))
; __device__ __forceinline__ int kswz(int key) { return ((key >> 1) & 1) | (((key >> 3) & 3) << 1); }
; template <bool LOC> ...
;     ...
;     for (int c = 0; c < 8; ++c) {
;         if (c < 7) AH_LDK(c + 1, (c + 1) & 1);
;         __builtin_amdgcn_sched_barrier(0);
;         f32x4 t0 = (f32x4){0.f, 0.f, 0.f, 0.f}, t1 = (f32x4){0.f, 0.f, 0.f, 0.f};
;         t0 = __builtin_amdgcn_mfma_f32_16x16x32_bf16(kf[c & 1][0], q0, t0, 0, 0, 0); t1 = __builtin_amdgcn_mfma_f32_16x16x32_bf16(kf[c & 1][2], q0, t1, 0, 0, 0);
;         t0 = __builtin_amdgcn_mfma_f32_16x16x32_bf16(kf[c & 1][1], q1, t0, 0, 0, 0); t1 = __builtin_amdgcn_mfma_f32_16x16x32_bf16(kf[c & 1][3], q1, t1, 0, 0, 0);
; #pragma unroll
;         for (int e = 0; e < 8; ++e) { const float a = (e < 4) ? t0[e] : t1[e - 4];
;             if (LOC) { const float bv = bp[c * RPB_PITCH + e]; const bool ok = (e >= elo) && (e < elo + 16); s[c][e] = ok ? (a * SC + bv) : -INFINITY; }
;             else s[c][e] = a * SC; }
;         __builtin_amdgcn_sched_barrier(0);
;     }
; __device__ __forceinline__ void phase_mixer(const Params& p, LAS unsigned char* lds, int l, bool with_ctx, int G, int tid, int wave, int lane, int rep_attn, int rep_pool) {
;     ...
;         {
;             u32x4 kreg[4], vreg[4];
;             const bf16_t* ksrc = PB + (size_t)(ML + b * CT + (tid >> 3)) * PBW + 1024 + h * 64 + (tid & 7) * 8;
;             const bf16_t* vsrc = VT + (size_t)(h * 64 + (tid >> 5)) * VTP + ML + b * CT + (tid & 31) * 8;
; #pragma unroll
;             for (int ps = 0; ps < 4; ++ps) { kreg[ps] = *(const u32x4*)(ksrc + (size_t)(ps * 64) * PBW); vreg[ps] = *(const u32x4*)(vsrc + (size_t)(ps * 16) * VTP); }
;             __builtin_amdgcn_sched_barrier(0);
; #pragma unroll
;             for (int ps = 0; ps < 4; ++ps) { const int key = ps * 64 + (tid >> 3), d = ps * 16 + (tid >> 5);
;                 *(LAS u32x4*)(lds + AT_KC + key * 128 + ((((tid & 7) ^ kswz(key))) << 4)) = kreg[ps];
;                 *(LAS u32x4*)(lds + AT_VC + d * 512 + ((((tid & 31) ^ (d & 15))) << 4)) = vreg[ps]; }
;         }
	v_pk_fma_f32 v[62:63], v[100:101], v[216:217], v[62:63]
	v_cndmask_b32_e64 v61, v222, v62, s[6:7]
	v_cndmask_b32_e64 v60, v222, v63, s[8:9]
	v_pk_fma_f32 v[210:211], v[102:103], v[216:217], v[210:211]
	v_cndmask_b32_e64 v63, v222, v210, s[10:11]
	v_cndmask_b32_e64 v62, v222, v211, s[12:13]
	v_pk_fma_f32 v[212:213], v[68:69], v[216:217], v[212:213]
	v_cndmask_b32_e64 v66, v222, v212, s[14:15]
	v_cndmask_b32_e64 v64, v222, v213, s[16:17]
	v_pk_fma_f32 v[214:215], v[70:71], v[216:217], v[214:215]
	v_cndmask_b32_e64 v102, v222, v214, s[18:19]
	v_cndmask_b32_e64 v100, v222, v215, s[20:21]
	ds_read_b128 v[178:181], v25 offset:49152
	ds_read_b128 v[190:193], v25 offset:49664
	ds_read_b128 v[194:197], v26 offset:49152
	ds_read_b128 v[198:201], v26 offset:49664
	v_mfma_f32_16x16x32_bf16 v[68:71], v[170:173], v[4:7], 0
	v_mfma_f32_16x16x32_bf16 v[170:173], v[182:185], v[0:3], v[68:71]
	v_mfma_f32_16x16x32_bf16 v[152:155], v[174:177], v[4:7], 0
	s_nop 4
	ds_read2_b32 v[70:71], v233 offset0:64 offset1:65
	ds_read2_b32 v[210:211], v233 offset0:66 offset1:67
	ds_read2_b32 v[212:213], v233 offset0:68 offset1:69
	ds_read2_b32 v[214:215], v233 offset0:70 offset1:71
	s_waitcnt lgkmcnt(0)
	v_pk_fma_f32 v[70:71], v[170:171], v[216:217], v[70:71]
	v_cndmask_b32_e64 v69, v222, v70, s[6:7]
	v_cndmask_b32_e64 v68, v222, v71, s[8:9]
	v_mfma_f32_16x16x32_bf16 v[174:177], v[186:189], v[0:3], v[152:155]
	v_pk_fma_f32 v[210:211], v[172:173], v[216:217], v[210:211]
	v_cndmask_b32_e64 v71, v222, v210, s[10:11]
	v_cndmask_b32_e64 v70, v222, v211, s[12:13]
	s_nop 3
	s_nop 0
	v_pk_fma_f32 v[212:213], v[174:175], v[216:217], v[212:213]
	v_cndmask_b32_e64 v101, v222, v212, s[14:15]
	v_cndmask_b32_e64 v99, v222, v213, s[16:17]
	v_pk_fma_f32 v[214:215], v[176:177], v[216:217], v[214:215]
	v_cndmask_b32_e64 v155, v222, v214, s[18:19]
	v_cndmask_b32_e64 v153, v222, v215, s[20:21]
	ds_read_b128 v[182:185], v25 offset:57344
	ds_read_b128 v[186:189], v25 offset:57856
	ds_read_b128 v[202:205], v26 offset:57344
	ds_read_b128 v[206:209], v26 offset:57856
	v_mfma_f32_16x16x32_bf16 v[170:173], v[178:181], v[4:7], 0
	ds_read2_b32 v[26:27], v233 offset0:128 offset1:129
	v_mfma_f32_16x16x32_bf16 v[170:173], v[194:197], v[0:3], v[170:173]
	v_mfma_f32_16x16x32_bf16 v[174:177], v[190:193], v[4:7], 0
	v_mfma_f32_16x16x32_bf16 v[174:177], v[198:201], v[0:3], v[174:177]
	ds_read2_b32 v[210:211], v233 offset0:130 offset1:131
	ds_read2_b32 v[212:213], v233 offset0:132 offset1:133
	ds_read2_b32 v[214:215], v233 offset0:134 offset1:135
	s_waitcnt lgkmcnt(0)
	s_nop 4
	v_pk_fma_f32 v[26:27], v[170:171], v[216:217], v[26:27]
	v_cndmask_b32_e64 v104, v222, v26, s[6:7]
	v_cndmask_b32_e64 v103, v222, v27, s[8:9]
	v_pk_fma_f32 v[210:211], v[172:173], v[216:217], v[210:211]
	v_cndmask_b32_e64 v151, v222, v210, s[10:11]
	v_cndmask_b32_e64 v105, v222, v211, s[12:13]
	v_pk_fma_f32 v[212:213], v[174:175], v[216:217], v[212:213]
	v_cndmask_b32_e64 v154, v222, v212, s[14:15]
	v_cndmask_b32_e64 v152, v222, v213, s[16:17]
	v_pk_fma_f32 v[214:215], v[176:177], v[216:217], v[214:215]
	v_cndmask_b32_e64 v175, v222, v214, s[18:19]
	v_cndmask_b32_e64 v173, v222, v215, s[20:21]
	v_mfma_f32_16x16x32_bf16 v[176:179], v[182:185], v[4:7], 0
	v_mfma_f32_16x16x32_bf16 v[4:7], v[186:189], v[4:7], 0
	v_mfma_f32_16x16x32_bf16 v[176:179], v[202:205], v[0:3], v[176:179]
	v_mfma_f32_16x16x32_bf16 v[0:3], v[206:209], v[0:3], v[4:7]
	s_nop 5
	ds_read2_b32 v[4:5], v233 offset0:192 offset1:193
	ds_read2_b32 v[210:211], v233 offset0:194 offset1:195
	ds_read2_b32 v[212:213], v233 offset0:196 offset1:197
	ds_read2_b32 v[214:215], v233 offset0:198 offset1:199
	s_waitcnt lgkmcnt(0)
	v_pk_fma_f32 v[4:5], v[176:177], v[216:217], v[4:5]
	v_cndmask_b32_e64 v170, v222, v4, s[6:7]
	v_cndmask_b32_e64 v167, v222, v5, s[8:9]
	v_pk_fma_f32 v[210:211], v[178:179], v[216:217], v[210:211]
	v_cndmask_b32_e64 v172, v222, v210, s[10:11]
	v_cndmask_b32_e64 v171, v222, v211, s[12:13]
	v_pk_fma_f32 v[212:213], v[0:1], v[216:217], v[212:213]
	v_cndmask_b32_e64 v176, v222, v212, s[14:15]
	v_cndmask_b32_e64 v174, v222, v213, s[16:17]
	v_pk_fma_f32 v[214:215], v[2:3], v[216:217], v[214:215]
	v_cndmask_b32_e64 v178, v222, v214, s[18:19]
	v_cndmask_b32_e64 v177, v222, v215, s[20:21]
	s_barrier
	s_add_i32 s94, s61, s3
	s_cmpk_gt_i32 s94, 0x7ff
	s_cbranch_scc1 .Lm_noctx
	s_lshr_b32 s95, s94, 8
	s_lshl_b32 s95, s95, 8
	s_add_i32 s95, s95, 0x8000
	s_mul_i32 s97, s95, 0xc00
	s_and_b32 s98, s94, 7
	s_lshl_b32 s99, s98, 7
	s_add_i32 s97, s97, s99
	s_add_i32 s97, s97, 0x800
	s_add_u32 s34, s0, s97
	s_addc_u32 s35, s1, 0
	s_lshl_b32 s99, s87, 10
	s_add_i32 m0, s99, 0x0
	s_nop 0
	global_load_lds_dwordx4 v235, s[34:35]
	s_add_u32 s34, s34, 0x30000
	s_addc_u32 s35, s35, 0
	s_add_i32 m0, s99, 0x2000
	s_nop 0
	global_load_lds_dwordx4 v235, s[34:35]
	s_add_u32 s34, s34, 0x30000
	s_addc_u32 s35, s35, 0
	s_add_i32 m0, s99, 0x4000
	s_nop 0
	global_load_lds_dwordx4 v235, s[34:35]
	s_add_u32 s34, s34, 0x30000
	s_addc_u32 s35, s35, 0
	s_add_i32 m0, s99, 0x6000
	s_nop 0
	global_load_lds_dwordx4 v235, s[34:35]
	s_mul_i32 s97, s98, 0x444000
	s_lshl_b32 s95, s95, 1
	s_add_i32 s97, s97, s95
	s_add_u32 s34, s28, s97
	s_addc_u32 s35, s29, 0
	s_add_i32 m0, s99, 0x8000
	s_nop 0
	global_load_lds_dwordx4 v236, s[34:35]
	s_add_u32 s34, s34, 0x111000
	s_addc_u32 s35, s35, 0
	s_add_i32 m0, s99, 0xa000
	s_nop 0
	global_load_lds_dwordx4 v236, s[34:35]
	s_add_u32 s34, s34, 0x111000
	s_addc_u32 s35, s35, 0
	s_add_i32 m0, s99, 0xc000
	s_nop 0
	global_load_lds_dwordx4 v236, s[34:35]
	s_add_u32 s34, s34, 0x111000
	s_addc_u32 s35, s35, 0
	s_add_i32 m0, s99, 0xe000
	s_nop 0
	global_load_lds_dwordx4 v236, s[34:35]
; __device__ __forceinline__ unsigned cvt_pk_bf16(float lo, float hi) { const f32x2 v = (f32x2){lo, hi}; return __builtin_bit_cast(unsigned, __builtin_convertvector(v, bf16v2)); }
; #define AH_LDV(c, bufi) do { const int vaddr = vrow + (((vchunk0 + (c) * vcs + g) ^ qi) << 4); _Pragma("unroll") for (int dt = 0; dt < 4; ++dt) vf[bufi][dt] = *(const LAS bf16x8*)(lds + vaddr + dt * vpitch_dt); } while (0)
; template <bool LOC> ...
;     ...
;     float m2 = mx;
; #pragma unroll
;     for (int c = 0; c < 8; ++c)
; #pragma unroll
;         for (int e = 0; e < 8; ++e) m2 = fmaxf(m2, s[c][e]);
;     m2 = fmaxf(m2, __shfl_xor(m2, 16)); m2 = fmaxf(m2, __shfl_xor(m2, 32));
;     const float alpha = __builtin_amdgcn_exp2f(mx - m2);
;     mx = m2; lsum *= alpha;
; #pragma unroll
;     for (int dt = 0; dt < 4; ++dt) o[dt] = o[dt] * alpha;
;     bf16x8 vf[2][4];
;     ...
;     AH_LDV(0, 0);
; #pragma unroll
;     for (int c = 0; c < 8; ++c) {
;         if (c < 7) AH_LDV(c + 1, (c + 1) & 1);
;         __builtin_amdgcn_sched_barrier(0);
;         float pe[8];
; #pragma unroll
;         for (int e = 0; e < 8; ++e) { pe[e] = __builtin_amdgcn_exp2f(s[c][e] - mx); lsum += pe[e]; }
;         u32x4 pw; pw.x = cvt_pk_bf16(pe[0], pe[1]); pw.y = cvt_pk_bf16(pe[2], pe[3]); pw.z = cvt_pk_bf16(pe[4], pe[5]); pw.w = cvt_pk_bf16(pe[6], pe[7]);
;         const bf16x8 pb = __builtin_bit_cast(bf16x8, pw);
; #pragma unroll
;         for (int dt = 0; dt < 4; ++dt) o[dt] = __builtin_amdgcn_mfma_f32_16x16x32_bf16(vf[c & 1][dt], pb, o[dt], 0, 0, 0);
;         __builtin_amdgcn_sched_barrier(0);
;     }
.Lm_noctx:
	v_max3_f32 v0, v97, v30, v29
	v_max3_f32 v0, v0, v32, v31
	v_max3_f32 v0, v0, v34, v33
	v_max3_f32 v0, v0, v43, v41
	v_max3_f32 v0, v0, v37, v35
	v_max3_f32 v0, v0, v39, v38
	v_max3_f32 v0, v0, v42, v40
	v_max3_f32 v0, v0, v51, v49
	v_max3_f32 v0, v0, v45, v44
	v_max3_f32 v0, v0, v47, v46
	v_max3_f32 v0, v0, v50, v48
	v_max3_f32 v0, v0, v59, v57
	v_max3_f32 v0, v0, v53, v52
	v_max3_f32 v0, v0, v55, v54
	v_max3_f32 v0, v0, v58, v56
	v_max3_f32 v0, v0, v67, v65
	v_max3_f32 v0, v0, v61, v60
	v_max3_f32 v0, v0, v63, v62
	v_max3_f32 v0, v0, v66, v64
	v_max3_f32 v0, v0, v102, v100
	v_max3_f32 v0, v0, v69, v68
	v_max3_f32 v0, v0, v71, v70
	v_max3_f32 v0, v0, v101, v99
	v_max3_f32 v0, v0, v155, v153
	v_max3_f32 v0, v0, v104, v103
	v_max3_f32 v0, v0, v151, v105
	v_max3_f32 v0, v0, v154, v152
	v_max3_f32 v0, v0, v175, v173
	v_max3_f32 v0, v0, v170, v167
	v_max3_f32 v0, v0, v172, v171
	v_max3_f32 v0, v0, v176, v174
	v_max3_f32 v0, v0, v178, v177
	ds_bpermute_b32 v1, v114, v0
	s_waitcnt lgkmcnt(0)
	v_max_f32_e32 v1, v1, v1
	v_max_f32_e32 v0, v0, v1
	ds_bpermute_b32 v1, v115, v0
	s_waitcnt lgkmcnt(0)
	v_max_f32_e32 v1, v1, v1
	v_max_f32_e32 v179, v0, v1
	v_sub_f32_e32 v0, v97, v179
	v_exp_f32_e32 v204, v0
	s_nop 0
	v_pk_mul_f32 v[24:25], v[8:9], v[204:205] op_sel_hi:[1,0]
	v_pk_mul_f32 v[8:9], v[12:13], v[204:205] op_sel_hi:[1,0]
	v_lshl_add_u32 v12, v36, 3, v112
	v_xor_b32_e32 v13, v12, v107
	v_lshl_add_u32 v13, v13, 4, v113
	v_pk_mul_f32 v[26:27], v[10:11], v[204:205] op_sel_hi:[1,0]
	v_pk_mul_f32 v[10:11], v[14:15], v[204:205] op_sel_hi:[1,0]
	v_pk_mul_f32 v[6:7], v[18:19], v[204:205] op_sel_hi:[1,0]
	v_pk_mul_f32 v[4:5], v[16:17], v[204:205] op_sel_hi:[1,0]
	v_pk_mul_f32 v[0:1], v[20:21], v[204:205] op_sel_hi:[1,0]
	ds_read_b128 v[14:17], v13
	ds_read_b128 v[18:21], v13 offset:20480
	ds_read_b128 v[180:183], v13 offset:40960
	ds_read_b128 v[184:187], v13 offset:61440
	v_add_u32_e32 v13, 8, v12
	v_xor_b32_e32 v13, v13, v107
	v_lshl_add_u32 v13, v13, 4, v113
	ds_read_b128 v[188:191], v13
	ds_read_b128 v[192:195], v13 offset:20480
	ds_read_b128 v[196:199], v13 offset:40960
	ds_read_b128 v[200:203], v13 offset:61440
	v_pk_mul_f32 v[2:3], v[22:23], v[204:205] op_sel_hi:[1,0]
	v_mul_f32_e32 v218, v28, v204
	v_mov_b32_e32 v219, 0
	v_sub_f32_e32 v224, v30, v179
	v_sub_f32_e32 v225, v29, v179
	v_exp_f32_e32 v224, v224
	v_sub_f32_e32 v226, v32, v179
	v_exp_f32_e32 v225, v225
	v_sub_f32_e32 v227, v31, v179
	v_exp_f32_e32 v226, v226
	v_sub_f32_e32 v228, v34, v179
	v_exp_f32_e32 v227, v227
	v_sub_f32_e32 v229, v33, v179
	v_exp_f32_e32 v228, v228
	v_pk_add_f32 v[218:219], v[218:219], v[224:225]
	v_sub_f32_e32 v230, v43, v179
	v_exp_f32_e32 v229, v229
	v_pk_add_f32 v[218:219], v[218:219], v[226:227]
	v_sub_f32_e32 v231, v41, v179
	v_exp_f32_e32 v230, v230
	v_cvt_pk_bf16_f32 v28, v224, v225
	v_exp_f32_e32 v231, v231
	v_cvt_pk_bf16_f32 v29, v226, v227
	v_pk_add_f32 v[218:219], v[218:219], v[228:229]
	v_cvt_pk_bf16_f32 v30, v228, v229
	v_cvt_pk_bf16_f32 v31, v230, v231
	v_pk_add_f32 v[218:219], v[218:219], v[230:231]
	s_waitcnt lgkmcnt(4)
	v_mfma_f32_16x16x32_bf16 v[14:17], v[14:17], v[28:31], v[24:27]
	v_mfma_f32_16x16x32_bf16 v[8:11], v[18:21], v[28:31], v[8:11]
	v_mfma_f32_16x16x32_bf16 v[4:7], v[180:183], v[28:31], v[4:7]
	v_mfma_f32_16x16x32_bf16 v[0:3], v[184:187], v[28:31], v[0:3]
	v_add_u32_e32 v13, 16, v12
	v_xor_b32_e32 v13, v13, v107
	v_lshl_add_u32 v13, v13, 4, v113
	ds_read_b128 v[18:21], v13
	ds_read_b128 v[22:25], v13 offset:20480
	ds_read_b128 v[26:29], v13 offset:40960
	ds_read_b128 v[30:33], v13 offset:61440
	v_sub_f32_e32 v224, v37, v179
	v_sub_f32_e32 v225, v35, v179
	v_exp_f32_e32 v224, v224
	v_sub_f32_e32 v226, v39, v179
	v_exp_f32_e32 v225, v225
	v_sub_f32_e32 v227, v38, v179
	v_exp_f32_e32 v226, v226
	v_sub_f32_e32 v228, v42, v179
	v_exp_f32_e32 v227, v227
	v_sub_f32_e32 v229, v40, v179
	v_exp_f32_e32 v228, v228
	v_pk_add_f32 v[218:219], v[218:219], v[224:225]
	v_sub_f32_e32 v230, v51, v179
	v_exp_f32_e32 v229, v229
	v_pk_add_f32 v[218:219], v[218:219], v[226:227]
	v_sub_f32_e32 v231, v49, v179
	v_exp_f32_e32 v230, v230
	v_cvt_pk_bf16_f32 v34, v224, v225
	v_exp_f32_e32 v231, v231
	v_cvt_pk_bf16_f32 v35, v226, v227
	v_pk_add_f32 v[218:219], v[218:219], v[228:229]
	v_cvt_pk_bf16_f32 v36, v228, v229
	v_cvt_pk_bf16_f32 v37, v230, v231
	v_pk_add_f32 v[218:219], v[218:219], v[230:231]
	s_waitcnt lgkmcnt(4)
	s_nop 0
	v_mfma_f32_16x16x32_bf16 v[14:17], v[188:191], v[34:37], v[14:17]
	v_mfma_f32_16x16x32_bf16 v[8:11], v[192:195], v[34:37], v[8:11]
	v_mfma_f32_16x16x32_bf16 v[4:7], v[196:199], v[34:37], v[4:7]
	v_mfma_f32_16x16x32_bf16 v[0:3], v[200:203], v[34:37], v[0:3]
	v_add_u32_e32 v13, 24, v12
	v_xor_b32_e32 v13, v13, v107
	v_lshl_add_u32 v13, v13, 4, v113
	ds_read_b128 v[34:37], v13
	ds_read_b128 v[38:41], v13 offset:20480
	ds_read_b128 v[180:183], v13 offset:40960
	ds_read_b128 v[184:187], v13 offset:61440
	v_sub_f32_e32 v224, v45, v179
	v_sub_f32_e32 v225, v44, v179
	v_exp_f32_e32 v224, v224
	v_sub_f32_e32 v226, v47, v179
	v_exp_f32_e32 v225, v225
	v_sub_f32_e32 v227, v46, v179
	v_exp_f32_e32 v226, v226
	v_sub_f32_e32 v228, v50, v179
	v_exp_f32_e32 v227, v227
	v_sub_f32_e32 v229, v48, v179
	v_exp_f32_e32 v228, v228
	v_pk_add_f32 v[218:219], v[218:219], v[224:225]
	v_sub_f32_e32 v230, v59, v179
	v_exp_f32_e32 v229, v229
	v_pk_add_f32 v[218:219], v[218:219], v[226:227]
	v_sub_f32_e32 v231, v57, v179
	v_exp_f32_e32 v230, v230
	v_cvt_pk_bf16_f32 v42, v224, v225
	v_exp_f32_e32 v231, v231
	v_cvt_pk_bf16_f32 v43, v226, v227
	v_pk_add_f32 v[218:219], v[218:219], v[228:229]
	v_cvt_pk_bf16_f32 v44, v228, v229
	v_cvt_pk_bf16_f32 v45, v230, v231
	v_pk_add_f32 v[218:219], v[218:219], v[230:231]
	s_waitcnt lgkmcnt(4)
; __device__ __forceinline__ unsigned cvt_pk_bf16(float lo, float hi) { const f32x2 v = (f32x2){lo, hi}; return __builtin_bit_cast(unsigned, __builtin_convertvector(v, bf16v2)); }
; #define AH_LDV(c, bufi) do { const int vaddr = vrow + (((vchunk0 + (c) * vcs + g) ^ qi) << 4); _Pragma("unroll") for (int dt = 0; dt < 4; ++dt) vf[bufi][dt] = *(const LAS bf16x8*)(lds + vaddr + dt * vpitch_dt); } while (0)
; template <bool LOC> ...
;     ...
;     for (int c = 0; c < 8; ++c) {
;         if (c < 7) AH_LDV(c + 1, (c + 1) & 1);
;         __builtin_amdgcn_sched_barrier(0);
;         float pe[8];
; #pragma unroll
;         for (int e = 0; e < 8; ++e) { pe[e] = __builtin_amdgcn_exp2f(s[c][e] - mx); lsum += pe[e]; }
;         u32x4 pw; pw.x = cvt_pk_bf16(pe[0], pe[1]); pw.y = cvt_pk_bf16(pe[2], pe[3]); pw.z = cvt_pk_bf16(pe[4], pe[5]); pw.w = cvt_pk_bf16(pe[6], pe[7]);
;         const bf16x8 pb = __builtin_bit_cast(bf16x8, pw);
; #pragma unroll
;         for (int dt = 0; dt < 4; ++dt) o[dt] = __builtin_amdgcn_mfma_f32_16x16x32_bf16(vf[c & 1][dt], pb, o[dt], 0, 0, 0);
;         __builtin_amdgcn_sched_barrier(0);
;     }
	s_nop 0
	v_mfma_f32_16x16x32_bf16 v[14:17], v[18:21], v[42:45], v[14:17]
	v_mfma_f32_16x16x32_bf16 v[8:11], v[22:25], v[42:45], v[8:11]
	v_mfma_f32_16x16x32_bf16 v[4:7], v[26:29], v[42:45], v[4:7]
	v_mfma_f32_16x16x32_bf16 v[0:3], v[30:33], v[42:45], v[0:3]
	v_add_u32_e32 v13, 32, v12
	v_xor_b32_e32 v13, v13, v107
	v_lshl_add_u32 v13, v13, 4, v113
	ds_read_b128 v[18:21], v13
	ds_read_b128 v[22:25], v13 offset:20480
	ds_read_b128 v[26:29], v13 offset:40960
	ds_read_b128 v[30:33], v13 offset:61440
	v_sub_f32_e32 v224, v53, v179
	v_sub_f32_e32 v225, v52, v179
	v_exp_f32_e32 v224, v224
	v_sub_f32_e32 v226, v55, v179
	v_exp_f32_e32 v225, v225
	v_sub_f32_e32 v227, v54, v179
	v_exp_f32_e32 v226, v226
	v_sub_f32_e32 v228, v58, v179
	v_exp_f32_e32 v227, v227
	v_sub_f32_e32 v229, v56, v179
	v_exp_f32_e32 v228, v228
	v_pk_add_f32 v[218:219], v[218:219], v[224:225]
	v_sub_f32_e32 v230, v67, v179
	v_exp_f32_e32 v229, v229
	v_pk_add_f32 v[218:219], v[218:219], v[226:227]
	v_sub_f32_e32 v231, v65, v179
	v_exp_f32_e32 v230, v230
	v_cvt_pk_bf16_f32 v42, v224, v225
	v_exp_f32_e32 v231, v231
	v_cvt_pk_bf16_f32 v43, v226, v227
	v_pk_add_f32 v[218:219], v[218:219], v[228:229]
	v_cvt_pk_bf16_f32 v44, v228, v229
	v_cvt_pk_bf16_f32 v45, v230, v231
	v_pk_add_f32 v[218:219], v[218:219], v[230:231]
	s_waitcnt lgkmcnt(4)
	s_nop 0
	v_mfma_f32_16x16x32_bf16 v[14:17], v[34:37], v[42:45], v[14:17]
	v_mfma_f32_16x16x32_bf16 v[8:11], v[38:41], v[42:45], v[8:11]
	v_mfma_f32_16x16x32_bf16 v[4:7], v[180:183], v[42:45], v[4:7]
	v_mfma_f32_16x16x32_bf16 v[0:3], v[184:187], v[42:45], v[0:3]
	v_add_u32_e32 v13, 40, v12
	v_xor_b32_e32 v13, v13, v107
	v_lshl_add_u32 v13, v13, 4, v113
	ds_read_b128 v[34:37], v13
	ds_read_b128 v[38:41], v13 offset:20480
	ds_read_b128 v[42:45], v13 offset:40960
	ds_read_b128 v[46:49], v13 offset:61440
	v_sub_f32_e32 v224, v61, v179
	v_sub_f32_e32 v225, v60, v179
	v_exp_f32_e32 v224, v224
	v_sub_f32_e32 v226, v63, v179
	v_exp_f32_e32 v225, v225
	v_sub_f32_e32 v227, v62, v179
	v_exp_f32_e32 v226, v226
	v_sub_f32_e32 v228, v66, v179
	v_exp_f32_e32 v227, v227
	v_sub_f32_e32 v229, v64, v179
	v_exp_f32_e32 v228, v228
	v_pk_add_f32 v[218:219], v[218:219], v[224:225]
	v_sub_f32_e32 v230, v102, v179
	v_exp_f32_e32 v229, v229
	v_pk_add_f32 v[218:219], v[218:219], v[226:227]
	v_sub_f32_e32 v231, v100, v179
	v_exp_f32_e32 v230, v230
	v_cvt_pk_bf16_f32 v50, v224, v225
	v_exp_f32_e32 v231, v231
	v_cvt_pk_bf16_f32 v51, v226, v227
	v_pk_add_f32 v[218:219], v[218:219], v[228:229]
	v_cvt_pk_bf16_f32 v52, v228, v229
	v_cvt_pk_bf16_f32 v53, v230, v231
	v_pk_add_f32 v[218:219], v[218:219], v[230:231]
	s_waitcnt lgkmcnt(4)
	s_nop 0
	v_mfma_f32_16x16x32_bf16 v[14:17], v[18:21], v[50:53], v[14:17]
	v_mfma_f32_16x16x32_bf16 v[8:11], v[22:25], v[50:53], v[8:11]
	v_mfma_f32_16x16x32_bf16 v[4:7], v[26:29], v[50:53], v[4:7]
	v_mfma_f32_16x16x32_bf16 v[0:3], v[30:33], v[50:53], v[0:3]
	v_add_u32_e32 v13, 48, v12
	v_xor_b32_e32 v13, v13, v107
	v_lshl_add_u32 v13, v13, 4, v113
	ds_read_b128 v[18:21], v13
	ds_read_b128 v[22:25], v13 offset:20480
	ds_read_b128 v[26:29], v13 offset:40960
	ds_read_b128 v[30:33], v13 offset:61440
	v_sub_f32_e32 v224, v69, v179
	v_sub_f32_e32 v225, v68, v179
	v_exp_f32_e32 v224, v224
	v_sub_f32_e32 v226, v71, v179
	v_exp_f32_e32 v225, v225
	v_sub_f32_e32 v227, v70, v179
	v_exp_f32_e32 v226, v226
	v_sub_f32_e32 v228, v101, v179
	v_exp_f32_e32 v227, v227
	v_sub_f32_e32 v229, v99, v179
	v_exp_f32_e32 v228, v228
	v_pk_add_f32 v[218:219], v[218:219], v[224:225]
	v_sub_f32_e32 v230, v155, v179
	v_exp_f32_e32 v229, v229
	v_pk_add_f32 v[218:219], v[218:219], v[226:227]
	v_sub_f32_e32 v231, v153, v179
	v_exp_f32_e32 v230, v230
	v_cvt_pk_bf16_f32 v50, v224, v225
	v_exp_f32_e32 v231, v231
	v_cvt_pk_bf16_f32 v51, v226, v227
	v_pk_add_f32 v[218:219], v[218:219], v[228:229]
	v_cvt_pk_bf16_f32 v52, v228, v229
	v_cvt_pk_bf16_f32 v53, v230, v231
	v_pk_add_f32 v[218:219], v[218:219], v[230:231]
	s_waitcnt lgkmcnt(4)
; __device__ __forceinline__ unsigned cvt_pk_bf16(float lo, float hi) { const f32x2 v = (f32x2){lo, hi}; return __builtin_bit_cast(unsigned, __builtin_convertvector(v, bf16v2)); }
; #define AH_LDV(c, bufi) do { const int vaddr = vrow + (((vchunk0 + (c) * vcs + g) ^ qi) << 4); _Pragma("unroll") for (int dt = 0; dt < 4; ++dt) vf[bufi][dt] = *(const LAS bf16x8*)(lds + vaddr + dt * vpitch_dt); } while (0)
; template <bool LOC> ...
;     ...
;     for (int c = 0; c < 8; ++c) {
;         if (c < 7) AH_LDV(c + 1, (c + 1) & 1);
;         __builtin_amdgcn_sched_barrier(0);
;         float pe[8];
; #pragma unroll
;         for (int e = 0; e < 8; ++e) { pe[e] = __builtin_amdgcn_exp2f(s[c][e] - mx); lsum += pe[e]; }
;         u32x4 pw; pw.x = cvt_pk_bf16(pe[0], pe[1]); pw.y = cvt_pk_bf16(pe[2], pe[3]); pw.z = cvt_pk_bf16(pe[4], pe[5]); pw.w = cvt_pk_bf16(pe[6], pe[7]);
;         const bf16x8 pb = __builtin_bit_cast(bf16x8, pw);
; #pragma unroll
;         for (int dt = 0; dt < 4; ++dt) o[dt] = __builtin_amdgcn_mfma_f32_16x16x32_bf16(vf[c & 1][dt], pb, o[dt], 0, 0, 0);
;         __builtin_amdgcn_sched_barrier(0);
;     }
;     ...
; }
; __device__ __forceinline__ void attn_store(bf16_t* MIX, int qtok, int h, int g, float lsum, const f32x4 (&o)[4]) {
;     lsum += __shfl_xor(lsum, 16); lsum += __shfl_xor(lsum, 32);
;     const float inv = 1.f / lsum;
;     bf16_t* op = MIX + (size_t)qtok * DM + 512 + h * 64 + 4 * g;
; #pragma unroll
;     for (int dt = 0; dt < 4; ++dt) { u32x2 w; w.x = cvt_pk_bf16(o[dt][0] * inv, o[dt][1] * inv); w.y = cvt_pk_bf16(o[dt][2] * inv, o[dt][3] * inv); *(u32x2*)(op + 16 * dt) = w; }
; }
; __device__ __forceinline__ void phase_mixer(const Params& p, LAS unsigned char* lds, int l, bool with_ctx, int G, int tid, int wave, int lane, int rep_attn, int rep_pool) {
;     ...
;             attn_store(MIX, b * SEQ + r * 64 + 16 * n + qi, h, g, lA, oA);
;         }
;         __syncthreads();
	s_nop 0
	v_mfma_f32_16x16x32_bf16 v[14:17], v[34:37], v[50:53], v[14:17]
	v_mfma_f32_16x16x32_bf16 v[8:11], v[38:41], v[50:53], v[8:11]
	v_mfma_f32_16x16x32_bf16 v[4:7], v[42:45], v[50:53], v[4:7]
	v_mfma_f32_16x16x32_bf16 v[0:3], v[46:49], v[50:53], v[0:3]
	v_add_u32_e32 v12, 56, v12
	v_xor_b32_e32 v12, v12, v107
	v_lshl_add_u32 v12, v12, 4, v113
	ds_read_b128 v[34:37], v12
	ds_read_b128 v[38:41], v12 offset:20480
	ds_read_b128 v[42:45], v12 offset:40960
	ds_read_b128 v[46:49], v12 offset:61440
	v_sub_f32_e32 v224, v104, v179
	v_sub_f32_e32 v225, v103, v179
	v_exp_f32_e32 v224, v224
	v_sub_f32_e32 v226, v151, v179
	v_exp_f32_e32 v225, v225
	v_sub_f32_e32 v227, v105, v179
	v_exp_f32_e32 v226, v226
	v_sub_f32_e32 v228, v154, v179
	v_exp_f32_e32 v227, v227
	v_sub_f32_e32 v229, v152, v179
	v_exp_f32_e32 v228, v228
	v_pk_add_f32 v[218:219], v[218:219], v[224:225]
	v_sub_f32_e32 v230, v175, v179
	v_exp_f32_e32 v229, v229
	v_pk_add_f32 v[218:219], v[218:219], v[226:227]
	v_sub_f32_e32 v231, v173, v179
	v_exp_f32_e32 v230, v230
	v_cvt_pk_bf16_f32 v50, v224, v225
	v_exp_f32_e32 v231, v231
	v_cvt_pk_bf16_f32 v51, v226, v227
	v_pk_add_f32 v[218:219], v[218:219], v[228:229]
	v_cvt_pk_bf16_f32 v52, v228, v229
	v_cvt_pk_bf16_f32 v53, v230, v231
	v_pk_add_f32 v[218:219], v[218:219], v[230:231]
	s_waitcnt lgkmcnt(4)
	v_mfma_f32_16x16x32_bf16 v[12:15], v[18:21], v[50:53], v[14:17]
	v_mfma_f32_16x16x32_bf16 v[8:11], v[22:25], v[50:53], v[8:11]
	v_mfma_f32_16x16x32_bf16 v[4:7], v[26:29], v[50:53], v[4:7]
	v_mfma_f32_16x16x32_bf16 v[0:3], v[30:33], v[50:53], v[0:3]
	v_sub_f32_e32 v224, v170, v179
	v_sub_f32_e32 v225, v167, v179
	v_exp_f32_e32 v224, v224
	v_sub_f32_e32 v226, v172, v179
	v_exp_f32_e32 v225, v225
	v_sub_f32_e32 v227, v171, v179
	v_exp_f32_e32 v226, v226
	v_sub_f32_e32 v228, v176, v179
	v_exp_f32_e32 v227, v227
	v_sub_f32_e32 v229, v174, v179
	v_exp_f32_e32 v228, v228
	v_pk_add_f32 v[218:219], v[218:219], v[224:225]
	v_sub_f32_e32 v230, v178, v179
	v_exp_f32_e32 v229, v229
	v_pk_add_f32 v[218:219], v[218:219], v[226:227]
	v_sub_f32_e32 v231, v177, v179
	v_exp_f32_e32 v230, v230
	v_cvt_pk_bf16_f32 v16, v224, v225
	v_exp_f32_e32 v231, v231
	v_cvt_pk_bf16_f32 v17, v226, v227
	v_pk_add_f32 v[218:219], v[218:219], v[228:229]
	v_cvt_pk_bf16_f32 v18, v228, v229
	v_cvt_pk_bf16_f32 v19, v230, v231
	v_pk_add_f32 v[218:219], v[218:219], v[230:231]
	v_add_f32_e32 v25, v218, v219
	s_waitcnt lgkmcnt(0)
	s_nop 0
	v_mfma_f32_16x16x32_bf16 v[12:15], v[34:37], v[16:19], v[12:15]
	v_mfma_f32_16x16x32_bf16 v[8:11], v[38:41], v[16:19], v[8:11]
	v_mfma_f32_16x16x32_bf16 v[4:7], v[42:45], v[16:19], v[4:7]
	v_mfma_f32_16x16x32_bf16 v[0:3], v[46:49], v[16:19], v[0:3]
	ds_bpermute_b32 v17, v114, v25
	v_or_b32_e32 v16, s62, v108
	v_mov_b32_e32 v99, v157
	s_add_i32 s61, s61, s3
	s_cmpk_gt_i32 s61, 0x7ff
	s_waitcnt lgkmcnt(0)
	v_add_f32_e32 v18, v25, v17
	ds_bpermute_b32 v19, v115, v18
	v_ashrrev_i32_e32 v17, 31, v16
	v_lshlrev_b64 v[16:17], 11, v[16:17]
	v_lshl_add_u64 v[16:17], s[26:27], 0, v[16:17]
	v_lshl_add_u64 v[16:17], v[16:17], 0, s[30:31]
	s_waitcnt lgkmcnt(0)
	v_add_f32_e32 v18, v18, v19
	v_div_scale_f32 v19, s[62:63], v18, v18, 1.0
	v_rcp_f32_e32 v20, v19
	v_div_scale_f32 v21, vcc, 1.0, v18, 1.0
	v_lshl_add_u64 v[16:17], v[16:17], 0, v[98:99]
	v_fma_f32 v22, -v19, v20, 1.0
	v_fmac_f32_e32 v20, v22, v20
	v_mul_f32_e32 v22, v21, v20
	v_fma_f32 v23, -v19, v22, v21
	v_fmac_f32_e32 v22, v23, v20
	v_fma_f32 v19, -v19, v22, v21
	v_div_fmas_f32 v19, v19, v20, v22
	v_div_fixup_f32 v18, v19, v18, 1.0
	v_pk_mul_f32 v[12:13], v[12:13], v[18:19] op_sel_hi:[1,0]
	v_pk_mul_f32 v[14:15], v[14:15], v[18:19] op_sel_hi:[1,0]
	v_pk_mul_f32 v[8:9], v[8:9], v[18:19] op_sel_hi:[1,0]
	v_pk_mul_f32 v[10:11], v[10:11], v[18:19] op_sel_hi:[1,0]
	v_pk_mul_f32 v[4:5], v[4:5], v[18:19] op_sel_hi:[1,0]
	v_pk_mul_f32 v[6:7], v[6:7], v[18:19] op_sel_hi:[1,0]
	v_pk_mul_f32 v[0:1], v[0:1], v[18:19] op_sel_hi:[1,0]
	v_pk_mul_f32 v[2:3], v[2:3], v[18:19] op_sel_hi:[1,0]
	v_cvt_pk_bf16_f32 v12, v12, v13
	v_cvt_pk_bf16_f32 v13, v14, v15
	v_cvt_pk_bf16_f32 v8, v8, v9
	v_cvt_pk_bf16_f32 v9, v10, v11
	v_cvt_pk_bf16_f32 v4, v4, v5
	v_cvt_pk_bf16_f32 v5, v6, v7
	v_cvt_pk_bf16_f32 v0, v0, v1
	v_cvt_pk_bf16_f32 v1, v2, v3
	global_store_dwordx2 v[16:17], v[12:13], off offset:1024
	global_store_dwordx2 v[16:17], v[8:9], off offset:1056
	global_store_dwordx2 v[16:17], v[4:5], off offset:1088
	global_store_dwordx2 v[16:17], v[0:1], off offset:1120
	s_cbranch_scc1 .LBB0_306

; #define LAS __attribute__((address_space(3)))
; __device__ __forceinline__ int kswz(int key) { return ((key >> 1) & 1) | (((key >> 3) & 3) << 1); }
; __device__ __forceinline__ void phase_mixer(const Params& p, LAS unsigned char* lds, int l, bool with_ctx, int G, int tid, int wave, int lane, int rep_attn, int rep_pool) {
;     ...
;             const int tok0 = b * SEQ + rs0 * 64;
;             const bf16_t* ksrc = PB + (size_t)(tok0 + (tid >> 3)) * PBW + 1024 + h * 64 + (tid & 7) * 8;
;             u32x4 kreg[9], vreg[9];
; #pragma unroll
;             for (int ps = 0; ps < 9; ++ps) { const int idx = ps * 512 + tid, d = idx / 72, ch = idx - d * 72;
;                 kreg[ps] = *(const u32x4*)(ksrc + (size_t)(ps * 64) * PBW);
;                 vreg[ps] = *(const u32x4*)(VT + (size_t)(h * 64 + d) * VTP + tok0 + ch * 8); }
;             __builtin_amdgcn_sched_barrier(0);
; #pragma unroll
;             for (int ps = 0; ps < 9; ++ps) { const int key = ps * 64 + (tid >> 3), idx = ps * 512 + tid, d = idx / 72, ch = idx - d * 72;
;                 *(LAS u32x4*)(lds + AT_KL + key * 128 + ((((tid & 7) ^ kswz(key))) << 4)) = kreg[ps];
;                 *(LAS u32x4*)(lds + AT_VL + d * AT_VLP + ((ch ^ (d & 15)) << 4)) = vreg[ps]; }
;             LAS float* rp = (LAS float*)(lds + AT_RPB);
;             for (int i = tid; i < 15 * RPB_PITCH; i += NTHR) { const int row = i >> 6, cc = (i & 63) - RPB_OFF; rp[i] = (cc >= 0 && cc < 31) ? p.in[I_RPB][(size_t)(l * 8 + h) * 15 * 31 + row * 31 + cc] * LOG2E : 0.f; }
.LBB0_301:
	v_sub_u32_e64 v24, s71, 4 clamp
	v_min_u32_e32 v26, 56, v24
	v_lshlrev_b32_e32 v24, 6, v26
	v_or_b32_e32 v24, s76, v24
	v_add_u32_e32 v25, v24, v109
	v_mov_b64_e32 v[30:31], s[0:1]
	v_mad_i64_i32 v[30:31], s[68:69], v25, s58, v[30:31]
	s_lshl_b32 s30, s70, 1
	v_lshl_add_u64 v[30:31], v[30:31], 0, s[30:31]
	v_lshl_add_u64 v[70:71], v[30:31], 0, v[156:157]
	s_mov_b32 s68, 0x30000
	v_add_co_u32_e32 v38, vcc, s68, v70
	s_nop 0
	v_addc_co_u32_e32 v39, vcc, 0, v71, vcc
	s_mov_b32 s68, 0x60000
	v_add_co_u32_e32 v46, vcc, s68, v70
	s_nop 0
	v_addc_co_u32_e32 v47, vcc, 0, v71, vcc
	s_mov_b32 s68, 0x90000
	v_add_co_u32_e32 v54, vcc, s68, v70
	s_nop 0
	v_addc_co_u32_e32 v55, vcc, 0, v71, vcc
	s_mov_b32 s68, 0xc0000
	v_add_co_u32_e32 v62, vcc, s68, v70
	s_nop 0
	v_addc_co_u32_e32 v63, vcc, 0, v71, vcc
	s_mov_b32 s68, 0xf0000
	v_add_co_u32_e32 v100, vcc, s68, v70
	v_addc_co_u32_e32 v101, vcc, 0, v71, vcc
	s_mov_b32 s68, 0x120000
	s_barrier
	global_load_dwordx4 v[30:33], v[70:71], off offset:2048
	s_nop 0
	s_nop 0
	global_load_dwordx4 v[38:41], v[38:39], off offset:2048
	s_nop 0
	s_nop 0
	global_load_dwordx4 v[46:49], v[46:47], off offset:2048
	s_nop 0
	s_nop 0
	global_load_dwordx4 v[54:57], v[54:55], off offset:2048
	s_nop 0
	s_nop 0
	global_load_dwordx4 v[62:65], v[62:63], off offset:2048
	s_nop 0
	s_nop 0
	global_load_dwordx4 v[100:103], v[100:101], off offset:2048
	s_nop 0
	v_add_co_u32_e32 v104, vcc, s68, v70
	s_nop 0
	v_addc_co_u32_e32 v105, vcc, 0, v71, vcc
	s_mov_b32 s68, 0x150000
	global_load_dwordx4 v[170:173], v[104:105], off offset:2048
	s_nop 0
	v_add_co_u32_e32 v104, vcc, s68, v70
	s_nop 0
	v_addc_co_u32_e32 v105, vcc, 0, v71, vcc
	s_mov_b32 s68, 0x180000
	v_add_co_u32_e32 v70, vcc, s68, v70
	v_addc_co_u32_e32 v71, vcc, 0, v71, vcc
	global_load_dwordx4 v[178:181], v[104:105], off offset:2048
	s_nop 0
	global_load_dwordx4 v[186:189], v[70:71], off offset:2048
	s_waitcnt vmcnt(8)
	ds_write_b128 v111, v[30:33]
	s_waitcnt vmcnt(7)
	ds_write_b128 v111, v[38:41] offset:8192
	s_waitcnt vmcnt(6)
	ds_write_b128 v111, v[46:49] offset:16384
	s_waitcnt vmcnt(5)
	ds_write_b128 v111, v[54:57] offset:24576
	s_waitcnt vmcnt(4)
	ds_write_b128 v111, v[62:65] offset:32768
	s_waitcnt vmcnt(3)
	ds_write_b128 v111, v[100:103] offset:40960
	s_waitcnt vmcnt(2)
	ds_write_b128 v111, v[170:173] offset:49152
	s_waitcnt vmcnt(1)
	ds_write_b128 v111, v[178:181] offset:57344
	s_waitcnt vmcnt(0)
	ds_write_b128 v125, v[186:189]
	s_mov_b32 s80, 0x3a800000
	s_mov_b64 s[68:69], exec
	s_cmp_eq_u32 s61, s2
	s_cbranch_scc1 .Lrpb_load
	s_and_b32 s32, s3, 7
	s_cmp_eq_u32 s32, 0
	s_cbranch_scc1 .LBB0_296

; __device__ __forceinline__ f32x4 bfx4_lo(u32x4 w) { return (f32x4){bf_lo(w.x), bf_hi(w.x), bf_lo(w.y), bf_hi(w.y)}; }
; __device__ __forceinline__ f32x4 bfx4_hi(u32x4 w) { return (f32x4){bf_lo(w.z), bf_hi(w.z), bf_lo(w.w), bf_hi(w.w)}; }
; __device__ __forceinline__ void phase_rows(const Params& p, const RowArgs& a, int G, int wave, int lane) {
;     ...
;         if (bmaj) mp = (it < ppw) ? (gw / wpb) * (SEQ / 2) + (gw % wpb) + it * wpb : ML / 2 + gw + (it - ppw) * NGW;
;         else mp = ((a.ctx_only && !bmaj) ? ML / 2 : 0) + gw + it * NGW;
;         if (mp >= a.nrows / 2) break;
;         const int m0 = 2 * mp; const bool isl = m0 < ML; const int rb = isl ? (m0 >> 12) : 8;
;         const bool use_y = a.has_y && !(a.lat_no_y && isl);
;         const size_t xoff = isl ? (size_t)m0 * DM : (size_t)(m0 - ML) * DM;
;         const void* xrb = isl ? a.xlat : a.xctx; void* xob = isl ? a.olat : a.octx;
;         bf16_t* xn = XN + (size_t)m0 * DM;
;         const size_t moff = (size_t)rb * NMOD;
;         f32x4 v[2][4], y[2][4];
;         if (a.xin_f32) {
; #pragma unroll
;             for (int u = 0; u < 2; ++u)
; #pragma unroll
;                 for (int j = 0; j < 4; ++j) v[u][j] = *(const f32x4*)((const float*)xrb + xoff + u * DM + 8 * lane + 512 * (j >> 1) + 4 * (j & 1));
;         } else {
; #pragma unroll
;             for (int u = 0; u < 2; ++u)
; #pragma unroll
;                 for (int jb = 0; jb < 2; ++jb) { const u32x4 xw = *(const u32x4*)((const bf16_t*)xrb + xoff + u * DM + 8 * lane + 512 * jb); v[u][2 * jb] = bfx4_lo(xw); v[u][2 * jb + 1] = bfx4_hi(xw); }
;     ...
;                 const float* part = (const float*)p.out;
; #pragma unroll
;                 for (int u = 0; u < 2; ++u)
; #pragma unroll
;                     for (int j = 0; j < 4; ++j) { const float* pp = part + (size_t)(m0 + u - ML) * DM + 8 * lane + 512 * (j >> 1) + 4 * (j & 1); f32x4 s = *(const f32x4*)pp;
; #pragma unroll
;                         for (int k = 1; k < pg8::KSPLIT; ++k) s += *(const f32x4*)(pp + (size_t)k * MC * DM);
;                         y[u][j] = s; }
.LBB0_327:
	s_cmpk_gt_i32 s11, 0x43ff
	s_mov_b64 s[0:1], -1
	s_cbranch_scc1 .LBB0_321
	s_lshl_b32 s4, s11, 1
	s_cmpk_lt_i32 s11, 0x4000
	s_cselect_b64 s[0:1], -1, 0
	s_ashr_i32 s5, s4, 31
	s_add_i32 s30, s4, 0xffff8000
	s_cmpk_gt_i32 s11, 0x3fff
	s_cselect_b64 s[8:9], -1, 0
	s_and_b64 s[6:7], s[8:9], exec
	s_cselect_b32 s7, 0, s5
	s_cselect_b32 s6, s30, s4
	s_cselect_b32 s21, s99, s79
	s_cselect_b32 s24, s98, s78
	s_lshl_b64 s[22:23], s[6:7], 11
	s_add_u32 s22, s24, s22
	s_addc_u32 s23, s21, s23
	global_load_dwordx4 v[116:119], v170, s[22:23] nt
	global_load_dwordx4 v[112:115], v170, s[22:23] offset:1024 nt
	global_load_dwordx4 v[108:111], v170, s[22:23] offset:2048 nt
	global_load_dwordx4 v[104:107], v170, s[22:23] offset:3072 nt
	s_and_b64 vcc, exec, s[0:1]
	s_cbranch_vccnz .LBB0_330
	s_lshl_b64 s[22:23], s[30:31], 12
	v_lshl_add_u64 v[88:89], v[176:177], 0, s[22:23]
	v_add_co_u32_e32 v96, vcc, 0x800000, v88
	global_load_dwordx4 v[84:87], v[88:89], off offset:16
	global_load_dwordx4 v[80:83], v[88:89], off
	s_mov_b64 s[24:25], 0x800000
	v_addc_co_u32_e32 v97, vcc, 0, v89, vcc
	v_lshl_add_u64 v[94:95], v[88:89], 0, s[24:25]
	global_load_dwordx4 v[90:93], v[96:97], off
	global_load_dwordx4 v[126:129], v[94:95], off offset:16
	s_mov_b64 s[26:27], 0x1000000
	v_add_co_u32_e32 v120, vcc, 0x1000000, v88
	s_mov_b64 s[28:29], 0x1800000
	s_nop 0
	v_addc_co_u32_e32 v121, vcc, 0, v89, vcc
	v_add_co_u32_e32 v122, vcc, 0x1800000, v88
	v_lshl_add_u64 v[100:101], v[88:89], 0, s[28:29]
	s_nop 0
	v_addc_co_u32_e32 v123, vcc, 0, v89, vcc
	v_add_co_u32_e32 v102, vcc, 0x2000000, v88
	s_mov_b64 s[34:35], 0x2000000
	s_nop 0
	v_addc_co_u32_e32 v103, vcc, 0, v89, vcc
	v_add_co_u32_e32 v124, vcc, 0x2800000, v88
	s_mov_b64 s[62:63], 0x2800000
	s_nop 0
	v_addc_co_u32_e32 v125, vcc, 0, v89, vcc
	s_mov_b64 s[64:65], 0x3000000
	v_lshl_add_u64 v[142:143], v[88:89], 0, s[64:65]
	s_mov_b64 s[68:69], 0x3800000
	v_lshl_add_u64 v[146:147], v[88:89], 0, s[68:69]
	s_mov_b64 s[70:71], 0x800800
	s_mov_b64 s[74:75], 0x1000800
	s_mov_b64 s[76:77], 0x1800800
	s_mov_b64 s[94:95], 0x2000800
	s_mov_b64 s[16:17], 0x2800800
	s_mov_b32 s38, s96
	s_mov_b64 s[96:97], 0x3000800
	s_mov_b64 s[36:37], 0x3800800
	s_add_i32 s30, s4, 0xffff8001
	s_lshl_b64 s[22:23], s[30:31], 12
	s_mov_b32 s21, 0x1000000
	s_waitcnt vmcnt(1)
	v_pk_add_f32 v[98:99], v[82:83], v[92:93]
	v_lshl_add_u64 v[92:93], v[88:89], 0, s[26:27]
	v_pk_add_f32 v[90:91], v[80:81], v[90:91]
	global_load_dwordx4 v[80:83], v[120:121], off
	s_nop 0
	global_load_dwordx4 v[92:95], v[92:93], off offset:16
	s_waitcnt vmcnt(2)
	v_pk_add_f32 v[86:87], v[86:87], v[128:129]
	v_pk_add_f32 v[84:85], v[84:85], v[126:127]
	s_waitcnt vmcnt(1)
	v_pk_add_f32 v[98:99], v[98:99], v[82:83]
	v_pk_add_f32 v[90:91], v[90:91], v[80:81]
	global_load_dwordx4 v[80:83], v[122:123], off
	global_load_dwordx4 v[130:133], v[100:101], off offset:16
	v_lshl_add_u64 v[100:101], v[88:89], 0, s[34:35]
	s_waitcnt vmcnt(2)
	v_pk_add_f32 v[86:87], v[86:87], v[94:95]
	v_pk_add_f32 v[84:85], v[84:85], v[92:93]
	s_waitcnt vmcnt(1)
	v_pk_add_f32 v[98:99], v[98:99], v[82:83]
	v_pk_add_f32 v[90:91], v[90:91], v[80:81]
	global_load_dwordx4 v[80:83], v[102:103], off
	global_load_dwordx4 v[134:137], v[100:101], off offset:16
	v_lshl_add_u64 v[100:101], v[88:89], 0, s[62:63]
	s_waitcnt vmcnt(2)
	v_pk_add_f32 v[86:87], v[86:87], v[132:133]
	v_pk_add_f32 v[84:85], v[84:85], v[130:131]
	s_waitcnt vmcnt(1)
	v_pk_add_f32 v[98:99], v[98:99], v[82:83]
	v_pk_add_f32 v[90:91], v[90:91], v[80:81]
	global_load_dwordx4 v[80:83], v[124:125], off
	global_load_dwordx4 v[138:141], v[100:101], off offset:16
	v_add_co_u32_e32 v100, vcc, 0x3000000, v88
	s_waitcnt vmcnt(2)
	v_pk_add_f32 v[86:87], v[86:87], v[136:137]
	v_addc_co_u32_e32 v101, vcc, 0, v89, vcc
	v_pk_add_f32 v[84:85], v[84:85], v[134:135]
	s_waitcnt vmcnt(1)
	v_pk_add_f32 v[98:99], v[98:99], v[82:83]
	v_pk_add_f32 v[90:91], v[90:91], v[80:81]
	global_load_dwordx4 v[80:83], v[100:101], off
	s_nop 0
	global_load_dwordx4 v[142:145], v[142:143], off offset:16
	s_waitcnt vmcnt(2)
	v_pk_add_f32 v[84:85], v[84:85], v[138:139]
	v_pk_add_f32 v[86:87], v[86:87], v[140:141]
	s_waitcnt vmcnt(1)
	v_pk_add_f32 v[150:151], v[90:91], v[80:81]
	v_add_co_u32_e32 v90, vcc, 0x3800000, v88
	v_pk_add_f32 v[98:99], v[98:99], v[82:83]
	s_nop 0
	v_addc_co_u32_e32 v91, vcc, 0, v89, vcc
	global_load_dwordx4 v[80:83], v[90:91], off
	s_nop 0
	global_load_dwordx4 v[146:149], v[146:147], off offset:16
	s_nop 0
	global_load_dwordx4 v[92:95], v[88:89], off offset:2064
	global_load_dwordx4 v[126:129], v[88:89], off offset:2048
	s_waitcnt vmcnt(4)
	v_pk_add_f32 v[84:85], v[84:85], v[142:143]
	v_pk_add_f32 v[86:87], v[86:87], v[144:145]
	s_waitcnt vmcnt(3)
	v_pk_add_f32 v[82:83], v[98:99], v[82:83]
	v_lshl_add_u64 v[98:99], v[88:89], 0, s[70:71]
	global_load_dwordx4 v[130:133], v[96:97], off offset:2048
	s_nop 0
	global_load_dwordx4 v[96:99], v[98:99], off offset:16
	s_waitcnt vmcnt(4)
	v_pk_add_f32 v[86:87], v[86:87], v[148:149]
	v_pk_add_f32 v[84:85], v[84:85], v[146:147]
	v_pk_add_f32 v[80:81], v[150:151], v[80:81]
	s_waitcnt vmcnt(1)
	v_pk_add_f32 v[136:137], v[126:127], v[130:131]
	v_lshl_add_u64 v[130:131], v[88:89], 0, s[74:75]
	v_pk_add_f32 v[134:135], v[128:129], v[132:133]
	global_load_dwordx4 v[126:129], v[120:121], off offset:2048
	s_nop 0
	global_load_dwordx4 v[130:133], v[130:131], off offset:16
	s_waitcnt vmcnt(2)
	v_pk_add_f32 v[92:93], v[92:93], v[96:97]
	v_pk_add_f32 v[94:95], v[94:95], v[98:99]
	s_waitcnt vmcnt(1)
; __device__ __forceinline__ void phase_rows(const Params& p, const RowArgs& a, int G, int wave, int lane) {
;     ...
;                 const float* part = (const float*)p.out;
; #pragma unroll
;                 for (int u = 0; u < 2; ++u)
; #pragma unroll
;                     for (int j = 0; j < 4; ++j) { const float* pp = part + (size_t)(m0 + u - ML) * DM + 8 * lane + 512 * (j >> 1) + 4 * (j & 1); f32x4 s = *(const f32x4*)pp;
; #pragma unroll
;                         for (int k = 1; k < pg8::KSPLIT; ++k) s += *(const f32x4*)(pp + (size_t)k * MC * DM);
;                         y[u][j] = s; }
	v_pk_add_f32 v[136:137], v[136:137], v[126:127]
	v_lshl_add_u64 v[126:127], v[88:89], 0, s[76:77]
	v_pk_add_f32 v[134:135], v[134:135], v[128:129]
	global_load_dwordx4 v[120:123], v[122:123], off offset:2048
	s_nop 0
	global_load_dwordx4 v[126:129], v[126:127], off offset:16
	s_waitcnt vmcnt(2)
	v_pk_add_f32 v[92:93], v[92:93], v[130:131]
	v_pk_add_f32 v[94:95], v[94:95], v[132:133]
	s_waitcnt vmcnt(1)
	v_pk_add_f32 v[138:139], v[134:135], v[122:123]
	v_lshl_add_u64 v[134:135], v[88:89], 0, s[94:95]
	v_pk_add_f32 v[140:141], v[136:137], v[120:121]
	global_load_dwordx4 v[120:123], v[102:103], off offset:2048
	s_nop 0
	global_load_dwordx4 v[134:137], v[134:135], off offset:16
	s_waitcnt vmcnt(2)
	v_pk_add_f32 v[92:93], v[92:93], v[126:127]
	v_pk_add_f32 v[94:95], v[94:95], v[128:129]
	s_waitcnt vmcnt(1)
	v_pk_add_f32 v[102:103], v[138:139], v[122:123]
	v_lshl_add_u64 v[138:139], v[88:89], 0, s[16:17]
	v_pk_add_f32 v[142:143], v[140:141], v[120:121]
	global_load_dwordx4 v[120:123], v[124:125], off offset:2048
	s_nop 0
	global_load_dwordx4 v[138:141], v[138:139], off offset:16
	s_waitcnt vmcnt(2)
	v_pk_add_f32 v[92:93], v[92:93], v[134:135]
	v_pk_add_f32 v[94:95], v[94:95], v[136:137]
	s_waitcnt vmcnt(1)
	v_pk_add_f32 v[142:143], v[142:143], v[120:121]
	v_lshl_add_u64 v[120:121], v[88:89], 0, s[96:97]
	v_pk_add_f32 v[124:125], v[102:103], v[122:123]
	global_load_dwordx4 v[100:103], v[100:101], off offset:2048
	s_nop 0
	global_load_dwordx4 v[120:123], v[120:121], off offset:16
	s_waitcnt vmcnt(2)
	v_pk_add_f32 v[92:93], v[92:93], v[138:139]
	v_pk_add_f32 v[94:95], v[94:95], v[140:141]
	s_waitcnt vmcnt(1)
	v_pk_add_f32 v[142:143], v[142:143], v[100:101]
	v_lshl_add_u64 v[100:101], v[88:89], 0, s[36:37]
	v_pk_add_f32 v[124:125], v[124:125], v[102:103]
	global_load_dwordx4 v[88:91], v[90:91], off offset:2048
	s_nop 0
	global_load_dwordx4 v[100:103], v[100:101], off offset:16
	s_waitcnt vmcnt(2)
	v_pk_add_f32 v[92:93], v[92:93], v[120:121]
	v_lshl_add_u64 v[120:121], v[176:177], 0, s[22:23]
	v_pk_add_f32 v[94:95], v[94:95], v[122:123]
	v_add_co_u32_e32 v122, vcc, s55, v120
	v_lshl_add_u64 v[128:129], v[120:121], 0, s[24:25]
	s_nop 0
	v_addc_co_u32_e32 v123, vcc, 0, v121, vcc
	v_add_co_u32_e32 v132, vcc, s21, v120
	s_mov_b32 s21, 0x1800000
	s_nop 0
	v_addc_co_u32_e32 v133, vcc, 0, v121, vcc
	v_lshl_add_u64 v[140:141], v[120:121], 0, s[28:29]
	s_waitcnt vmcnt(1)
	v_pk_add_f32 v[90:91], v[124:125], v[90:91]
	s_waitcnt vmcnt(0)
	v_pk_add_f32 v[94:95], v[94:95], v[102:103]
	v_pk_add_f32 v[92:93], v[92:93], v[100:101]
	global_load_dwordx4 v[100:103], v[120:121], off offset:16
	global_load_dwordx4 v[96:99], v[120:121], off
	global_load_dwordx4 v[124:127], v[122:123], off
	s_nop 0
	global_load_dwordx4 v[128:131], v[128:129], off offset:16
	v_pk_add_f32 v[88:89], v[142:143], v[88:89]
	v_lshl_add_u64 v[142:143], v[120:121], 0, s[34:35]
	s_waitcnt vmcnt(1)
	v_pk_add_f32 v[136:137], v[96:97], v[124:125]
	v_lshl_add_u64 v[124:125], v[120:121], 0, s[26:27]
	v_pk_add_f32 v[134:135], v[98:99], v[126:127]
	global_load_dwordx4 v[96:99], v[132:133], off
	s_nop 0
	global_load_dwordx4 v[124:127], v[124:125], off offset:16
	s_waitcnt vmcnt(2)
	v_pk_add_f32 v[102:103], v[102:103], v[130:131]
	v_pk_add_f32 v[100:101], v[100:101], v[128:129]
	v_lshl_add_u64 v[128:129], v[120:121], 0, s[70:71]
	s_waitcnt vmcnt(1)
	v_pk_add_f32 v[138:139], v[136:137], v[96:97]
	v_add_co_u32_e32 v136, vcc, s21, v120
	v_pk_add_f32 v[134:135], v[134:135], v[98:99]
	s_nop 0
	v_addc_co_u32_e32 v137, vcc, 0, v121, vcc
	global_load_dwordx4 v[96:99], v[136:137], off
	global_load_dwordx4 v[178:181], v[140:141], off offset:16
	s_brev_b32 s21, 64
	v_add_co_u32_e32 v140, vcc, s21, v120
	s_mov_b32 s21, 0x2800000
	s_nop 0
	v_addc_co_u32_e32 v141, vcc, 0, v121, vcc
	v_add_co_u32_e32 v144, vcc, s21, v120
	s_mov_b32 s21, 0x3000000
	s_nop 0
	v_addc_co_u32_e32 v145, vcc, 0, v121, vcc
	v_add_co_u32_e32 v148, vcc, s21, v120
	s_mov_b32 s21, 0x3800000
	s_nop 0
	v_addc_co_u32_e32 v149, vcc, 0, v121, vcc
	v_add_co_u32_e32 v152, vcc, s21, v120
	s_waitcnt vmcnt(2)
	v_pk_add_f32 v[102:103], v[102:103], v[126:127]
	v_addc_co_u32_e32 v153, vcc, 0, v121, vcc
	v_pk_add_f32 v[100:101], v[100:101], v[124:125]
	s_waitcnt vmcnt(1)
	v_pk_add_f32 v[134:135], v[134:135], v[98:99]
	v_pk_add_f32 v[138:139], v[138:139], v[96:97]
	global_load_dwordx4 v[96:99], v[140:141], off
	global_load_dwordx4 v[182:185], v[142:143], off offset:16
	v_lshl_add_u64 v[142:143], v[120:121], 0, s[62:63]
	s_waitcnt vmcnt(2)
; __device__ __forceinline__ void phase_rows(const Params& p, const RowArgs& a, int G, int wave, int lane) {
;     ...
;                 const float* part = (const float*)p.out;
; #pragma unroll
;                 for (int u = 0; u < 2; ++u)
; #pragma unroll
;                     for (int j = 0; j < 4; ++j) { const float* pp = part + (size_t)(m0 + u - ML) * DM + 8 * lane + 512 * (j >> 1) + 4 * (j & 1); f32x4 s = *(const f32x4*)pp;
; #pragma unroll
;                         for (int k = 1; k < pg8::KSPLIT; ++k) s += *(const f32x4*)(pp + (size_t)k * MC * DM);
;                         y[u][j] = s; }
	v_pk_add_f32 v[102:103], v[102:103], v[180:181]
	v_pk_add_f32 v[100:101], v[100:101], v[178:179]
	s_waitcnt vmcnt(1)
	v_pk_add_f32 v[134:135], v[134:135], v[98:99]
	v_pk_add_f32 v[138:139], v[138:139], v[96:97]
	global_load_dwordx4 v[96:99], v[144:145], off
	global_load_dwordx4 v[186:189], v[142:143], off offset:16
	v_lshl_add_u64 v[142:143], v[120:121], 0, s[64:65]
	s_waitcnt vmcnt(2)
	v_pk_add_f32 v[102:103], v[102:103], v[184:185]
	v_pk_add_f32 v[100:101], v[100:101], v[182:183]
	s_waitcnt vmcnt(1)
	v_pk_add_f32 v[134:135], v[134:135], v[98:99]
	v_pk_add_f32 v[138:139], v[138:139], v[96:97]
	global_load_dwordx4 v[96:99], v[148:149], off
	global_load_dwordx4 v[190:193], v[142:143], off offset:16
	v_lshl_add_u64 v[142:143], v[120:121], 0, s[68:69]
	s_waitcnt vmcnt(2)
	v_pk_add_f32 v[102:103], v[102:103], v[188:189]
	v_pk_add_f32 v[100:101], v[100:101], v[186:187]
	s_waitcnt vmcnt(1)
	v_pk_add_f32 v[134:135], v[134:135], v[98:99]
	v_pk_add_f32 v[138:139], v[138:139], v[96:97]
	global_load_dwordx4 v[96:99], v[152:153], off
	global_load_dwordx4 v[194:197], v[142:143], off offset:16
	global_load_dwordx4 v[124:127], v[120:121], off offset:2064
	global_load_dwordx4 v[178:181], v[120:121], off offset:2048
	global_load_dwordx4 v[182:185], v[122:123], off offset:2048
	s_nop 0
	global_load_dwordx4 v[128:131], v[128:129], off offset:16
	s_waitcnt vmcnt(6)
	v_pk_add_f32 v[102:103], v[102:103], v[192:193]
	v_pk_add_f32 v[100:101], v[100:101], v[190:191]
	s_waitcnt vmcnt(5)
	v_pk_add_f32 v[98:99], v[134:135], v[98:99]
	v_lshl_add_u64 v[134:135], v[120:121], 0, s[74:75]
	v_pk_add_f32 v[96:97], v[138:139], v[96:97]
	s_waitcnt vmcnt(1)
	v_pk_add_f32 v[122:123], v[180:181], v[184:185]
	v_pk_add_f32 v[138:139], v[178:179], v[182:183]
	global_load_dwordx4 v[178:181], v[132:133], off offset:2048
	s_nop 0
	global_load_dwordx4 v[132:135], v[134:135], off offset:16
	s_waitcnt vmcnt(2)
	v_pk_add_f32 v[126:127], v[126:127], v[130:131]
	v_pk_add_f32 v[124:125], v[124:125], v[128:129]
	v_pk_add_f32 v[102:103], v[102:103], v[196:197]
	v_pk_add_f32 v[100:101], v[100:101], v[194:195]
	s_waitcnt vmcnt(1)
	v_pk_add_f32 v[142:143], v[138:139], v[178:179]
	v_lshl_add_u64 v[138:139], v[120:121], 0, s[76:77]
	v_pk_add_f32 v[122:123], v[122:123], v[180:181]
	global_load_dwordx4 v[178:181], v[136:137], off offset:2048
	s_nop 0
	global_load_dwordx4 v[136:139], v[138:139], off offset:16
	s_waitcnt vmcnt(2)
	v_pk_add_f32 v[126:127], v[126:127], v[134:135]
	v_pk_add_f32 v[124:125], v[124:125], v[132:133]
	s_waitcnt vmcnt(1)
	v_pk_add_f32 v[146:147], v[142:143], v[178:179]
	v_lshl_add_u64 v[142:143], v[120:121], 0, s[94:95]
	v_pk_add_f32 v[122:123], v[122:123], v[180:181]
	global_load_dwordx4 v[178:181], v[140:141], off offset:2048
	s_nop 0
	global_load_dwordx4 v[140:143], v[142:143], off offset:16
	s_waitcnt vmcnt(2)
	v_pk_add_f32 v[126:127], v[126:127], v[138:139]
	v_pk_add_f32 v[124:125], v[124:125], v[136:137]
	v_readlane_b32 s94, v255, 27
	v_readlane_b32 s95, v255, 28
	s_waitcnt vmcnt(1)
	v_pk_add_f32 v[150:151], v[146:147], v[178:179]
	v_lshl_add_u64 v[146:147], v[120:121], 0, s[16:17]
	v_pk_add_f32 v[122:123], v[122:123], v[180:181]
	global_load_dwordx4 v[178:181], v[144:145], off offset:2048
	s_nop 0
	global_load_dwordx4 v[144:147], v[146:147], off offset:16
	s_waitcnt vmcnt(2)
	v_pk_add_f32 v[126:127], v[126:127], v[142:143]
	v_pk_add_f32 v[124:125], v[124:125], v[140:141]
	s_waitcnt vmcnt(1)
	v_pk_add_f32 v[154:155], v[150:151], v[178:179]
	v_lshl_add_u64 v[150:151], v[120:121], 0, s[96:97]
	v_pk_add_f32 v[122:123], v[122:123], v[180:181]
	global_load_dwordx4 v[180:183], v[148:149], off offset:2048
	s_nop 0
	global_load_dwordx4 v[148:151], v[150:151], off offset:16
	s_waitcnt vmcnt(2)
	v_pk_add_f32 v[126:127], v[126:127], v[146:147]
	v_pk_add_f32 v[124:125], v[124:125], v[144:145]
	s_mov_b32 s96, s38
	s_waitcnt vmcnt(1)
	v_pk_add_f32 v[180:181], v[154:155], v[180:181]
	v_lshl_add_u64 v[154:155], v[120:121], 0, s[36:37]
	v_pk_add_f32 v[178:179], v[122:123], v[182:183]
	global_load_dwordx4 v[120:123], v[152:153], off offset:2048
	s_nop 0
	global_load_dwordx4 v[152:155], v[154:155], off offset:16
	s_waitcnt vmcnt(2)
	v_pk_add_f32 v[126:127], v[126:127], v[150:151]
	v_pk_add_f32 v[124:125], v[124:125], v[148:149]
	s_waitcnt vmcnt(1)
	v_pk_add_f32 v[122:123], v[178:179], v[122:123]
	v_pk_add_f32 v[120:121], v[180:181], v[120:121]
	s_waitcnt vmcnt(0)
	v_pk_add_f32 v[126:127], v[126:127], v[154:155]
	v_pk_add_f32 v[124:125], v[124:125], v[152:153]
